# v58 + GEMM K-loops: loop-carried pointer/counter SALU and the exit compare moved in front of the loop-back barrier (back-edge trim)
# baseline (speedup 1.0000x reference)
.LBB0_541:
	s_add_u32 s6, s4, 0xfffc0080
	s_addc_u32 s7, s5, -1
	s_add_i32 s61, 0, 0x10000
	s_cmp_eq_u32 s17, 12
	s_cselect_b32 s9, s11, s7
	s_cselect_b32 s8, s12, s6
	v_add_u32_e32 v2, s61, v167
	s_cselect_b32 s7, s13, s16
	s_cselect_b32 s6, s14, s15
	s_add_i32 s77, 0, 0x14000
	ds_read_b128 v[132:135], v2
	ds_read_b128 v[148:151], v2 offset:1024
	ds_read_b128 v[152:155], v2 offset:2048
	ds_read_b128 v[156:159], v2 offset:3072
	v_add_u32_e32 v2, s77, v167
	ds_read_b128 v[160:163], v2
	ds_read_b128 v[170:173], v2 offset:1024
	ds_read_b128 v[174:177], v2 offset:2048
	ds_read_b128 v[178:181], v2 offset:3072
	v_lshl_add_u64 v[164:165], s[4:5], 0, v[144:145]
	s_add_i32 m0, s84, 0xc000
	ds_read_b128 v[182:185], v168
	ds_read_b128 v[186:189], v168 offset:1024
	ds_read_b128 v[190:193], v168 offset:2048
	ds_read_b128 v[194:197], v168 offset:3072
	ds_read_b128 v[198:201], v168 offset:4096
	ds_read_b128 v[202:205], v168 offset:5120
	ds_read_b128 v[218:221], v168 offset:6144
	ds_read_b128 v[222:225], v168 offset:7168
	global_load_lds_dwordx4 v[164:165], off
	v_lshl_add_u64 v[164:165], s[4:5], 0, v[146:147]
	s_add_i32 m0, s84, 0xe000
	s_nop 0
	global_load_lds_dwordx4 v[164:165], off
	s_waitcnt vmcnt(8)
	s_waitcnt lgkmcnt(0)
	s_barrier
	s_waitcnt lgkmcnt(0)
	v_mfma_f32_16x16x32_bf16 v[128:131], v[132:135], v[182:185], v[128:131]
	v_mfma_f32_16x16x32_bf16 v[124:127], v[152:155], v[182:185], v[124:127]
	v_mfma_f32_16x16x32_bf16 v[112:115], v[132:135], v[190:193], v[112:115]
	v_mfma_f32_16x16x32_bf16 v[108:111], v[152:155], v[190:193], v[108:111]
	v_mfma_f32_16x16x32_bf16 v[96:99], v[132:135], v[198:201], v[96:99]
	v_mfma_f32_16x16x32_bf16 v[92:95], v[152:155], v[198:201], v[92:95]
	v_mfma_f32_16x16x32_bf16 v[80:83], v[132:135], v[218:221], v[80:83]
	v_mfma_f32_16x16x32_bf16 v[76:79], v[152:155], v[218:221], v[76:79]
	v_mfma_f32_16x16x32_bf16 v[128:131], v[148:151], v[186:189], v[128:131]
	v_mfma_f32_16x16x32_bf16 v[124:127], v[156:159], v[186:189], v[124:127]
	v_mfma_f32_16x16x32_bf16 v[112:115], v[148:151], v[194:197], v[112:115]
	v_mfma_f32_16x16x32_bf16 v[108:111], v[156:159], v[194:197], v[108:111]
	v_mfma_f32_16x16x32_bf16 v[96:99], v[148:151], v[202:205], v[96:99]
	v_mfma_f32_16x16x32_bf16 v[92:95], v[156:159], v[202:205], v[92:95]
	v_mfma_f32_16x16x32_bf16 v[80:83], v[148:151], v[222:225], v[80:83]
	v_mfma_f32_16x16x32_bf16 v[76:79], v[156:159], v[222:225], v[76:79]
	v_mfma_f32_16x16x32_bf16 v[120:123], v[160:163], v[182:185], v[120:123]
	v_mfma_f32_16x16x32_bf16 v[116:119], v[174:177], v[182:185], v[116:119]
	v_mfma_f32_16x16x32_bf16 v[104:107], v[160:163], v[190:193], v[104:107]
	v_mfma_f32_16x16x32_bf16 v[100:103], v[174:177], v[190:193], v[100:103]
	v_mfma_f32_16x16x32_bf16 v[88:91], v[160:163], v[198:201], v[88:91]
	v_mfma_f32_16x16x32_bf16 v[84:87], v[174:177], v[198:201], v[84:87]
	v_mfma_f32_16x16x32_bf16 v[72:75], v[160:163], v[218:221], v[72:75]
	v_mfma_f32_16x16x32_bf16 v[68:71], v[174:177], v[218:221], v[68:71]
	v_mfma_f32_16x16x32_bf16 v[120:123], v[170:173], v[186:189], v[120:123]
	v_mfma_f32_16x16x32_bf16 v[116:119], v[178:181], v[186:189], v[116:119]
	v_mfma_f32_16x16x32_bf16 v[104:107], v[170:173], v[194:197], v[104:107]
	v_mfma_f32_16x16x32_bf16 v[100:103], v[178:181], v[194:197], v[100:103]
	v_mfma_f32_16x16x32_bf16 v[88:91], v[170:173], v[202:205], v[88:91]
	v_mfma_f32_16x16x32_bf16 v[84:87], v[178:181], v[202:205], v[84:87]
	v_mfma_f32_16x16x32_bf16 v[72:75], v[170:173], v[222:225], v[72:75]
	v_mfma_f32_16x16x32_bf16 v[68:71], v[178:181], v[222:225], v[68:71]
	s_barrier
	s_add_i32 s18, s61, s83
	v_lshl_add_u64 v[164:165], s[6:7], 0, v[138:139]
	s_mov_b32 m0, s18
	ds_read_b128 v[182:185], v168 offset:16384
	ds_read_b128 v[186:189], v168 offset:17408
	ds_read_b128 v[190:193], v168 offset:18432
	ds_read_b128 v[194:197], v168 offset:19456
	ds_read_b128 v[198:201], v168 offset:20480
	ds_read_b128 v[202:205], v168 offset:21504
	ds_read_b128 v[218:221], v168 offset:22528
	ds_read_b128 v[222:225], v168 offset:23552
	global_load_lds_dwordx4 v[164:165], off
	s_add_i32 m0, s18, 0x2000
	s_add_u32 s18, s6, 0x40000
	v_lshl_add_u64 v[206:207], s[6:7], 0, v[142:143]
	s_addc_u32 s19, s7, 0
	s_add_i32 s21, s77, s83
	global_load_lds_dwordx4 v[206:207], off
	v_lshl_add_u64 v[210:211], s[18:19], 0, v[138:139]
	s_mov_b32 m0, s21
	v_lshl_add_u64 v[212:213], s[8:9], 0, v[140:141]
	global_load_lds_dwordx4 v[210:211], off
	v_lshl_add_u64 v[210:211], s[18:19], 0, v[142:143]
	s_add_i32 m0, s21, 0x2000
	s_nop 0
	global_load_lds_dwordx4 v[210:211], off
	v_lshl_add_u64 v[210:211], s[8:9], 0, v[136:137]
	s_mov_b32 m0, s84
	s_nop 0
	global_load_lds_dwordx4 v[210:211], off
	s_mov_b32 m0, s85
	s_nop 0
	global_load_lds_dwordx4 v[212:213], off
	s_waitcnt vmcnt(8)
	s_waitcnt lgkmcnt(0)
	s_barrier
	s_waitcnt lgkmcnt(0)
	v_mfma_f32_16x16x32_bf16 v[64:67], v[132:135], v[182:185], v[64:67]
	v_mfma_f32_16x16x32_bf16 v[60:63], v[152:155], v[182:185], v[60:63]
	v_mfma_f32_16x16x32_bf16 v[48:51], v[132:135], v[190:193], v[48:51]
	v_mfma_f32_16x16x32_bf16 v[44:47], v[152:155], v[190:193], v[44:47]
	v_mfma_f32_16x16x32_bf16 v[32:35], v[132:135], v[198:201], v[32:35]
	v_mfma_f32_16x16x32_bf16 v[28:31], v[152:155], v[198:201], v[28:31]
	v_mfma_f32_16x16x32_bf16 v[16:19], v[132:135], v[218:221], v[16:19]
	v_mfma_f32_16x16x32_bf16 v[12:15], v[152:155], v[218:221], v[12:15]
	v_mfma_f32_16x16x32_bf16 v[64:67], v[148:151], v[186:189], v[64:67]
	v_mfma_f32_16x16x32_bf16 v[60:63], v[156:159], v[186:189], v[60:63]
	v_mfma_f32_16x16x32_bf16 v[48:51], v[148:151], v[194:197], v[48:51]
	v_mfma_f32_16x16x32_bf16 v[44:47], v[156:159], v[194:197], v[44:47]
	v_mfma_f32_16x16x32_bf16 v[32:35], v[148:151], v[202:205], v[32:35]
	v_mfma_f32_16x16x32_bf16 v[28:31], v[156:159], v[202:205], v[28:31]
	v_mfma_f32_16x16x32_bf16 v[16:19], v[148:151], v[222:225], v[16:19]
	v_mfma_f32_16x16x32_bf16 v[12:15], v[156:159], v[222:225], v[12:15]
	v_mfma_f32_16x16x32_bf16 v[56:59], v[160:163], v[182:185], v[56:59]
	v_mfma_f32_16x16x32_bf16 v[52:55], v[174:177], v[182:185], v[52:55]
	v_mfma_f32_16x16x32_bf16 v[40:43], v[160:163], v[190:193], v[40:43]
	v_mfma_f32_16x16x32_bf16 v[36:39], v[174:177], v[190:193], v[36:39]
	v_mfma_f32_16x16x32_bf16 v[24:27], v[160:163], v[198:201], v[24:27]
	v_mfma_f32_16x16x32_bf16 v[20:23], v[174:177], v[198:201], v[20:23]
	v_mfma_f32_16x16x32_bf16 v[8:11], v[160:163], v[218:221], v[8:11]
	v_mfma_f32_16x16x32_bf16 v[4:7], v[174:177], v[218:221], v[4:7]
	v_mfma_f32_16x16x32_bf16 v[56:59], v[170:173], v[186:189], v[56:59]
	v_mfma_f32_16x16x32_bf16 v[52:55], v[178:181], v[186:189], v[52:55]
	v_mfma_f32_16x16x32_bf16 v[40:43], v[170:173], v[194:197], v[40:43]
	v_mfma_f32_16x16x32_bf16 v[36:39], v[178:181], v[194:197], v[36:39]
	v_mfma_f32_16x16x32_bf16 v[24:27], v[170:173], v[202:205], v[24:27]
	v_mfma_f32_16x16x32_bf16 v[20:23], v[178:181], v[202:205], v[20:23]
	v_mfma_f32_16x16x32_bf16 v[8:11], v[170:173], v[222:225], v[8:11]
	v_mfma_f32_16x16x32_bf16 v[4:7], v[178:181], v[222:225], v[4:7]
	s_barrier
	s_add_i32 s79, 0, 0x18000
	v_add_u32_e32 v2, s79, v167
	s_add_i32 s80, 0, 0x1c000
	ds_read_b128 v[132:135], v2
	ds_read_b128 v[148:151], v2 offset:1024
	ds_read_b128 v[152:155], v2 offset:2048
	ds_read_b128 v[156:159], v2 offset:3072
	v_add_u32_e32 v2, s80, v167
	ds_read_b128 v[160:163], v2
	ds_read_b128 v[170:173], v2 offset:1024
	ds_read_b128 v[174:177], v2 offset:2048
	ds_read_b128 v[178:181], v2 offset:3072
	s_add_u32 s8, s8, 0x40000
	s_addc_u32 s9, s9, 0
	s_mov_b32 m0, s68
	v_lshl_add_u64 v[226:227], s[8:9], 0, v[136:137]
	ds_read_b128 v[182:185], v168 offset:32768
	ds_read_b128 v[186:189], v168 offset:33792
	ds_read_b128 v[190:193], v168 offset:34816
	ds_read_b128 v[194:197], v168 offset:35840
	ds_read_b128 v[198:201], v168 offset:36864
	ds_read_b128 v[202:205], v168 offset:37888
	ds_read_b128 v[218:221], v168 offset:38912
	ds_read_b128 v[222:225], v168 offset:39936
	global_load_lds_dwordx4 v[226:227], off
	v_lshl_add_u64 v[226:227], s[8:9], 0, v[140:141]
	s_mov_b32 m0, s69
	s_nop 0
	global_load_lds_dwordx4 v[226:227], off
	s_waitcnt vmcnt(8)
	s_waitcnt lgkmcnt(0)
	s_barrier
	s_waitcnt lgkmcnt(0)
	v_mfma_f32_16x16x32_bf16 v[128:131], v[132:135], v[182:185], v[128:131]
	v_mfma_f32_16x16x32_bf16 v[124:127], v[152:155], v[182:185], v[124:127]
	v_mfma_f32_16x16x32_bf16 v[112:115], v[132:135], v[190:193], v[112:115]
	v_mfma_f32_16x16x32_bf16 v[108:111], v[152:155], v[190:193], v[108:111]
	v_mfma_f32_16x16x32_bf16 v[96:99], v[132:135], v[198:201], v[96:99]
	v_mfma_f32_16x16x32_bf16 v[92:95], v[152:155], v[198:201], v[92:95]
	v_mfma_f32_16x16x32_bf16 v[80:83], v[132:135], v[218:221], v[80:83]
	v_mfma_f32_16x16x32_bf16 v[76:79], v[152:155], v[218:221], v[76:79]
	v_mfma_f32_16x16x32_bf16 v[128:131], v[148:151], v[186:189], v[128:131]
	v_mfma_f32_16x16x32_bf16 v[124:127], v[156:159], v[186:189], v[124:127]
	v_mfma_f32_16x16x32_bf16 v[112:115], v[148:151], v[194:197], v[112:115]
	v_mfma_f32_16x16x32_bf16 v[108:111], v[156:159], v[194:197], v[108:111]
	v_mfma_f32_16x16x32_bf16 v[96:99], v[148:151], v[202:205], v[96:99]
	v_mfma_f32_16x16x32_bf16 v[92:95], v[156:159], v[202:205], v[92:95]
	v_mfma_f32_16x16x32_bf16 v[80:83], v[148:151], v[222:225], v[80:83]
	v_mfma_f32_16x16x32_bf16 v[76:79], v[156:159], v[222:225], v[76:79]
	v_mfma_f32_16x16x32_bf16 v[120:123], v[160:163], v[182:185], v[120:123]
	v_mfma_f32_16x16x32_bf16 v[116:119], v[174:177], v[182:185], v[116:119]
	v_mfma_f32_16x16x32_bf16 v[104:107], v[160:163], v[190:193], v[104:107]
	v_mfma_f32_16x16x32_bf16 v[100:103], v[174:177], v[190:193], v[100:103]
	v_mfma_f32_16x16x32_bf16 v[88:91], v[160:163], v[198:201], v[88:91]
	v_mfma_f32_16x16x32_bf16 v[84:87], v[174:177], v[198:201], v[84:87]
	v_mfma_f32_16x16x32_bf16 v[72:75], v[160:163], v[218:221], v[72:75]
	v_mfma_f32_16x16x32_bf16 v[68:71], v[174:177], v[218:221], v[68:71]
	v_mfma_f32_16x16x32_bf16 v[120:123], v[170:173], v[186:189], v[120:123]
	v_mfma_f32_16x16x32_bf16 v[116:119], v[178:181], v[186:189], v[116:119]
	v_mfma_f32_16x16x32_bf16 v[104:107], v[170:173], v[194:197], v[104:107]
	v_mfma_f32_16x16x32_bf16 v[100:103], v[178:181], v[194:197], v[100:103]
	v_mfma_f32_16x16x32_bf16 v[88:91], v[170:173], v[202:205], v[88:91]
	v_mfma_f32_16x16x32_bf16 v[84:87], v[178:181], v[202:205], v[84:87]
	v_mfma_f32_16x16x32_bf16 v[72:75], v[170:173], v[222:225], v[72:75]
	v_mfma_f32_16x16x32_bf16 v[68:71], v[178:181], v[222:225], v[68:71]
	s_barrier
	s_add_i32 s8, s79, s83
	v_lshl_add_u64 v[164:165], v[164:165], 0, s[56:57]
	s_mov_b32 m0, s8
	ds_read_b128 v[182:185], v168 offset:49152
	ds_read_b128 v[186:189], v168 offset:50176
	ds_read_b128 v[190:193], v168 offset:51200
	ds_read_b128 v[194:197], v168 offset:52224
	ds_read_b128 v[198:201], v168 offset:53248
	ds_read_b128 v[202:205], v168 offset:54272
	ds_read_b128 v[218:221], v168 offset:55296
	ds_read_b128 v[222:225], v168 offset:56320
	global_load_lds_dwordx4 v[164:165], off
	s_add_i32 m0, s8, 0x2000
	s_add_u32 s6, s6, 0x40080
	v_lshl_add_u64 v[164:165], v[206:207], 0, s[56:57]
	s_addc_u32 s7, s7, 0
	s_add_i32 s8, s80, s83
	global_load_lds_dwordx4 v[164:165], off
	v_lshl_add_u64 v[164:165], s[6:7], 0, v[138:139]
	s_mov_b32 m0, s8
	s_nop 0
	global_load_lds_dwordx4 v[164:165], off
	v_lshl_add_u64 v[164:165], s[6:7], 0, v[142:143]
	s_add_i32 m0, s8, 0x2000
	s_nop 0
	global_load_lds_dwordx4 v[164:165], off
	v_lshl_add_u64 v[164:165], v[210:211], 0, s[56:57]
	s_mov_b32 m0, s72
	s_nop 0
	global_load_lds_dwordx4 v[164:165], off
	v_lshl_add_u64 v[164:165], v[212:213], 0, s[56:57]
	s_mov_b32 m0, s73
	s_nop 0
	global_load_lds_dwordx4 v[164:165], off
	s_waitcnt vmcnt(8)
	s_waitcnt lgkmcnt(0)
	s_barrier
	s_waitcnt lgkmcnt(0)
	v_mfma_f32_16x16x32_bf16 v[64:67], v[132:135], v[182:185], v[64:67]
	v_mfma_f32_16x16x32_bf16 v[60:63], v[152:155], v[182:185], v[60:63]
	v_mfma_f32_16x16x32_bf16 v[48:51], v[132:135], v[190:193], v[48:51]
	v_mfma_f32_16x16x32_bf16 v[44:47], v[152:155], v[190:193], v[44:47]
	v_mfma_f32_16x16x32_bf16 v[32:35], v[132:135], v[198:201], v[32:35]
	v_mfma_f32_16x16x32_bf16 v[28:31], v[152:155], v[198:201], v[28:31]
	v_mfma_f32_16x16x32_bf16 v[16:19], v[132:135], v[218:221], v[16:19]
	v_mfma_f32_16x16x32_bf16 v[12:15], v[152:155], v[218:221], v[12:15]
	v_mfma_f32_16x16x32_bf16 v[64:67], v[148:151], v[186:189], v[64:67]
	v_mfma_f32_16x16x32_bf16 v[60:63], v[156:159], v[186:189], v[60:63]
	v_mfma_f32_16x16x32_bf16 v[48:51], v[148:151], v[194:197], v[48:51]
	v_mfma_f32_16x16x32_bf16 v[44:47], v[156:159], v[194:197], v[44:47]
	v_mfma_f32_16x16x32_bf16 v[32:35], v[148:151], v[202:205], v[32:35]
	v_mfma_f32_16x16x32_bf16 v[28:31], v[156:159], v[202:205], v[28:31]
	v_mfma_f32_16x16x32_bf16 v[16:19], v[148:151], v[222:225], v[16:19]
	v_mfma_f32_16x16x32_bf16 v[12:15], v[156:159], v[222:225], v[12:15]
	v_mfma_f32_16x16x32_bf16 v[56:59], v[160:163], v[182:185], v[56:59]
	v_mfma_f32_16x16x32_bf16 v[52:55], v[174:177], v[182:185], v[52:55]
	v_mfma_f32_16x16x32_bf16 v[40:43], v[160:163], v[190:193], v[40:43]
	v_mfma_f32_16x16x32_bf16 v[36:39], v[174:177], v[190:193], v[36:39]
	v_mfma_f32_16x16x32_bf16 v[24:27], v[160:163], v[198:201], v[24:27]
	v_mfma_f32_16x16x32_bf16 v[20:23], v[174:177], v[198:201], v[20:23]
	v_mfma_f32_16x16x32_bf16 v[8:11], v[160:163], v[218:221], v[8:11]
	v_mfma_f32_16x16x32_bf16 v[4:7], v[174:177], v[218:221], v[4:7]
	v_mfma_f32_16x16x32_bf16 v[56:59], v[170:173], v[186:189], v[56:59]
	v_mfma_f32_16x16x32_bf16 v[52:55], v[178:181], v[186:189], v[52:55]
	v_mfma_f32_16x16x32_bf16 v[40:43], v[170:173], v[194:197], v[40:43]
	v_mfma_f32_16x16x32_bf16 v[36:39], v[178:181], v[194:197], v[36:39]
	v_mfma_f32_16x16x32_bf16 v[24:27], v[170:173], v[202:205], v[24:27]
	v_mfma_f32_16x16x32_bf16 v[20:23], v[178:181], v[202:205], v[20:23]
	v_mfma_f32_16x16x32_bf16 v[8:11], v[170:173], v[222:225], v[8:11]
	v_mfma_f32_16x16x32_bf16 v[4:7], v[178:181], v[222:225], v[4:7]
	s_add_i32 s17, s17, 2
	s_add_u32 s4, s4, 0x100
	s_addc_u32 s5, s5, 0
	s_add_u32 s15, s15, 0x100
	s_addc_u32 s16, s16, 0
	s_cmp_gt_u32 s17, 13
	s_barrier
	s_cbranch_scc0 .LBB0_541
	s_and_b64 vcc, exec, s[58:59]
	s_cbranch_vccz .LBB0_544
	s_barrier

.LBB0_985:
	v_add_u32_e32 v158, s61, v144
	v_add_u32_e32 v174, s77, v144
	s_add_u32 s8, s20, s6
	ds_read_b128 v[146:149], v158
	ds_read_b128 v[150:153], v158 offset:1024
	ds_read_b128 v[154:157], v158 offset:2048
	ds_read_b128 v[158:161], v158 offset:3072
	ds_read_b128 v[162:165], v174
	ds_read_b128 v[166:169], v174 offset:1024
	ds_read_b128 v[170:173], v174 offset:2048
	ds_read_b128 v[174:177], v174 offset:3072
	s_addc_u32 s9, s21, s7
	s_add_u32 s8, s8, 0x4000100
	s_addc_u32 s9, s9, 0
	s_add_u32 s25, s22, s6
	s_addc_u32 s26, s23, s7
	s_cmpk_eq_i32 s6, 0x700
	s_cselect_b32 s11, s3, s9
	s_cselect_b32 s10, s2, s8
	s_cselect_b32 s9, s1, s26
	s_cselect_b32 s8, s0, s25
	v_lshl_add_u64 v[206:207], v[140:141], 0, s[6:7]
	s_add_i32 m0, s5, 0xc000
	ds_read_b128 v[178:181], v145
	ds_read_b128 v[182:185], v145 offset:1024
	ds_read_b128 v[186:189], v145 offset:2048
	ds_read_b128 v[190:193], v145 offset:3072
	ds_read_b128 v[194:197], v145 offset:4096
	ds_read_b128 v[198:201], v145 offset:5120
	ds_read_b128 v[202:205], v145 offset:6144
	ds_read_b128 v[218:221], v145 offset:7168
	global_load_lds_dwordx4 v[206:207], off
	v_lshl_add_u64 v[206:207], v[142:143], 0, s[6:7]
	s_add_i32 m0, s5, 0xe000
	s_nop 0
	global_load_lds_dwordx4 v[206:207], off
	s_waitcnt vmcnt(8)
	s_waitcnt lgkmcnt(0)
	s_barrier
	s_waitcnt lgkmcnt(0)
	v_mfma_f32_16x16x32_bf16 v[128:131], v[146:149], v[178:181], v[128:131]
	v_mfma_f32_16x16x32_bf16 v[124:127], v[154:157], v[178:181], v[124:127]
	v_mfma_f32_16x16x32_bf16 v[112:115], v[146:149], v[186:189], v[112:115]
	v_mfma_f32_16x16x32_bf16 v[108:111], v[154:157], v[186:189], v[108:111]
	v_mfma_f32_16x16x32_bf16 v[96:99], v[146:149], v[194:197], v[96:99]
	v_mfma_f32_16x16x32_bf16 v[92:95], v[154:157], v[194:197], v[92:95]
	v_mfma_f32_16x16x32_bf16 v[80:83], v[146:149], v[202:205], v[80:83]
	v_mfma_f32_16x16x32_bf16 v[76:79], v[154:157], v[202:205], v[76:79]
	v_mfma_f32_16x16x32_bf16 v[128:131], v[150:153], v[182:185], v[128:131]
	v_mfma_f32_16x16x32_bf16 v[124:127], v[158:161], v[182:185], v[124:127]
	v_mfma_f32_16x16x32_bf16 v[112:115], v[150:153], v[190:193], v[112:115]
	v_mfma_f32_16x16x32_bf16 v[108:111], v[158:161], v[190:193], v[108:111]
	v_mfma_f32_16x16x32_bf16 v[96:99], v[150:153], v[198:201], v[96:99]
	v_mfma_f32_16x16x32_bf16 v[92:95], v[158:161], v[198:201], v[92:95]
	v_mfma_f32_16x16x32_bf16 v[80:83], v[150:153], v[218:221], v[80:83]
	v_mfma_f32_16x16x32_bf16 v[76:79], v[158:161], v[218:221], v[76:79]
	v_mfma_f32_16x16x32_bf16 v[120:123], v[162:165], v[178:181], v[120:123]
	v_mfma_f32_16x16x32_bf16 v[116:119], v[170:173], v[178:181], v[116:119]
	v_mfma_f32_16x16x32_bf16 v[104:107], v[162:165], v[186:189], v[104:107]
	v_mfma_f32_16x16x32_bf16 v[100:103], v[170:173], v[186:189], v[100:103]
	v_mfma_f32_16x16x32_bf16 v[88:91], v[162:165], v[194:197], v[88:91]
	v_mfma_f32_16x16x32_bf16 v[84:87], v[170:173], v[194:197], v[84:87]
	v_mfma_f32_16x16x32_bf16 v[72:75], v[162:165], v[202:205], v[72:75]
	v_mfma_f32_16x16x32_bf16 v[68:71], v[170:173], v[202:205], v[68:71]
	v_mfma_f32_16x16x32_bf16 v[120:123], v[166:169], v[182:185], v[120:123]
	v_mfma_f32_16x16x32_bf16 v[116:119], v[174:177], v[182:185], v[116:119]
	v_mfma_f32_16x16x32_bf16 v[104:107], v[166:169], v[190:193], v[104:107]
	v_mfma_f32_16x16x32_bf16 v[100:103], v[174:177], v[190:193], v[100:103]
	v_mfma_f32_16x16x32_bf16 v[88:91], v[166:169], v[198:201], v[88:91]
	v_mfma_f32_16x16x32_bf16 v[84:87], v[174:177], v[198:201], v[84:87]
	v_mfma_f32_16x16x32_bf16 v[72:75], v[166:169], v[218:221], v[72:75]
	v_mfma_f32_16x16x32_bf16 v[68:71], v[174:177], v[218:221], v[68:71]
	s_barrier
	s_add_i32 s25, s61, s13
	v_lshl_add_u64 v[206:207], s[8:9], 0, v[136:137]
	s_mov_b32 m0, s25
	ds_read_b128 v[178:181], v145 offset:16384
	ds_read_b128 v[182:185], v145 offset:17408
	ds_read_b128 v[186:189], v145 offset:18432
	ds_read_b128 v[190:193], v145 offset:19456
	ds_read_b128 v[194:197], v145 offset:20480
	ds_read_b128 v[198:201], v145 offset:21504
	ds_read_b128 v[202:205], v145 offset:22528
	ds_read_b128 v[218:221], v145 offset:23552
	global_load_lds_dwordx4 v[206:207], off
	s_add_i32 m0, s25, 0x2000
	s_add_u32 s26, s8, 0x40000
	v_lshl_add_u64 v[210:211], s[8:9], 0, v[132:133]
	s_addc_u32 s27, s9, 0
	s_add_i32 s25, s77, s13
	global_load_lds_dwordx4 v[210:211], off
	v_lshl_add_u64 v[212:213], s[26:27], 0, v[136:137]
	s_mov_b32 m0, s25
	v_lshl_add_u64 v[222:223], s[10:11], 0, v[134:135]
	global_load_lds_dwordx4 v[212:213], off
	v_lshl_add_u64 v[212:213], s[26:27], 0, v[132:133]
	s_add_i32 m0, s25, 0x2000
	s_nop 0
	global_load_lds_dwordx4 v[212:213], off
	v_lshl_add_u64 v[212:213], s[10:11], 0, v[138:139]
	s_mov_b32 m0, s5
	s_nop 0
	global_load_lds_dwordx4 v[212:213], off
	s_mov_b32 m0, s15
	s_nop 0
	global_load_lds_dwordx4 v[222:223], off
	s_waitcnt vmcnt(8)
	s_waitcnt lgkmcnt(0)
	s_barrier
	s_waitcnt lgkmcnt(0)
	v_mfma_f32_16x16x32_bf16 v[64:67], v[146:149], v[178:181], v[64:67]
	v_mfma_f32_16x16x32_bf16 v[60:63], v[154:157], v[178:181], v[60:63]
	v_mfma_f32_16x16x32_bf16 v[48:51], v[146:149], v[186:189], v[48:51]
	v_mfma_f32_16x16x32_bf16 v[44:47], v[154:157], v[186:189], v[44:47]
	v_mfma_f32_16x16x32_bf16 v[32:35], v[146:149], v[194:197], v[32:35]
	v_mfma_f32_16x16x32_bf16 v[28:31], v[154:157], v[194:197], v[28:31]
	v_mfma_f32_16x16x32_bf16 v[16:19], v[146:149], v[202:205], v[16:19]
	v_mfma_f32_16x16x32_bf16 v[12:15], v[154:157], v[202:205], v[12:15]
	v_mfma_f32_16x16x32_bf16 v[64:67], v[150:153], v[182:185], v[64:67]
	v_mfma_f32_16x16x32_bf16 v[60:63], v[158:161], v[182:185], v[60:63]
	v_mfma_f32_16x16x32_bf16 v[48:51], v[150:153], v[190:193], v[48:51]
	v_mfma_f32_16x16x32_bf16 v[44:47], v[158:161], v[190:193], v[44:47]
	v_mfma_f32_16x16x32_bf16 v[32:35], v[150:153], v[198:201], v[32:35]
	v_mfma_f32_16x16x32_bf16 v[28:31], v[158:161], v[198:201], v[28:31]
	v_mfma_f32_16x16x32_bf16 v[16:19], v[150:153], v[218:221], v[16:19]
	v_mfma_f32_16x16x32_bf16 v[12:15], v[158:161], v[218:221], v[12:15]
	v_mfma_f32_16x16x32_bf16 v[56:59], v[162:165], v[178:181], v[56:59]
	v_mfma_f32_16x16x32_bf16 v[52:55], v[170:173], v[178:181], v[52:55]
	v_mfma_f32_16x16x32_bf16 v[40:43], v[162:165], v[186:189], v[40:43]
	v_mfma_f32_16x16x32_bf16 v[36:39], v[170:173], v[186:189], v[36:39]
	v_mfma_f32_16x16x32_bf16 v[24:27], v[162:165], v[194:197], v[24:27]
	v_mfma_f32_16x16x32_bf16 v[20:23], v[170:173], v[194:197], v[20:23]
	v_mfma_f32_16x16x32_bf16 v[8:11], v[162:165], v[202:205], v[8:11]
	v_mfma_f32_16x16x32_bf16 v[4:7], v[170:173], v[202:205], v[4:7]
	v_mfma_f32_16x16x32_bf16 v[56:59], v[166:169], v[182:185], v[56:59]
	v_mfma_f32_16x16x32_bf16 v[52:55], v[174:177], v[182:185], v[52:55]
	v_mfma_f32_16x16x32_bf16 v[40:43], v[166:169], v[190:193], v[40:43]
	v_mfma_f32_16x16x32_bf16 v[36:39], v[174:177], v[190:193], v[36:39]
	v_mfma_f32_16x16x32_bf16 v[24:27], v[166:169], v[198:201], v[24:27]
	v_mfma_f32_16x16x32_bf16 v[20:23], v[174:177], v[198:201], v[20:23]
	v_mfma_f32_16x16x32_bf16 v[8:11], v[166:169], v[218:221], v[8:11]
	v_mfma_f32_16x16x32_bf16 v[4:7], v[174:177], v[218:221], v[4:7]
	s_barrier
	v_add_u32_e32 v158, s79, v144
	v_add_u32_e32 v174, s80, v144
	ds_read_b128 v[146:149], v158
	ds_read_b128 v[150:153], v158 offset:1024
	ds_read_b128 v[154:157], v158 offset:2048
	ds_read_b128 v[158:161], v158 offset:3072
	ds_read_b128 v[162:165], v174
	ds_read_b128 v[166:169], v174 offset:1024
	ds_read_b128 v[170:173], v174 offset:2048
	ds_read_b128 v[174:177], v174 offset:3072
	s_add_u32 s10, s10, 0x40000
	s_addc_u32 s11, s11, 0
	s_mov_b32 m0, s16
	v_lshl_add_u64 v[224:225], s[10:11], 0, v[138:139]
	ds_read_b128 v[178:181], v145 offset:32768
	ds_read_b128 v[182:185], v145 offset:33792
	ds_read_b128 v[186:189], v145 offset:34816
	ds_read_b128 v[190:193], v145 offset:35840
	ds_read_b128 v[194:197], v145 offset:36864
	ds_read_b128 v[198:201], v145 offset:37888
	ds_read_b128 v[202:205], v145 offset:38912
	ds_read_b128 v[218:221], v145 offset:39936
	global_load_lds_dwordx4 v[224:225], off
	v_lshl_add_u64 v[224:225], s[10:11], 0, v[134:135]
	s_mov_b32 m0, s17
	s_nop 0
	global_load_lds_dwordx4 v[224:225], off
	s_waitcnt vmcnt(8)
	s_waitcnt lgkmcnt(0)
	s_barrier
	s_waitcnt lgkmcnt(0)
	v_mfma_f32_16x16x32_bf16 v[128:131], v[146:149], v[178:181], v[128:131]
	v_mfma_f32_16x16x32_bf16 v[124:127], v[154:157], v[178:181], v[124:127]
	v_mfma_f32_16x16x32_bf16 v[112:115], v[146:149], v[186:189], v[112:115]
	v_mfma_f32_16x16x32_bf16 v[108:111], v[154:157], v[186:189], v[108:111]
	v_mfma_f32_16x16x32_bf16 v[96:99], v[146:149], v[194:197], v[96:99]
	v_mfma_f32_16x16x32_bf16 v[92:95], v[154:157], v[194:197], v[92:95]
	v_mfma_f32_16x16x32_bf16 v[80:83], v[146:149], v[202:205], v[80:83]
	v_mfma_f32_16x16x32_bf16 v[76:79], v[154:157], v[202:205], v[76:79]
	v_mfma_f32_16x16x32_bf16 v[128:131], v[150:153], v[182:185], v[128:131]
	v_mfma_f32_16x16x32_bf16 v[124:127], v[158:161], v[182:185], v[124:127]
	v_mfma_f32_16x16x32_bf16 v[112:115], v[150:153], v[190:193], v[112:115]
	v_mfma_f32_16x16x32_bf16 v[108:111], v[158:161], v[190:193], v[108:111]
	v_mfma_f32_16x16x32_bf16 v[96:99], v[150:153], v[198:201], v[96:99]
	v_mfma_f32_16x16x32_bf16 v[92:95], v[158:161], v[198:201], v[92:95]
	v_mfma_f32_16x16x32_bf16 v[80:83], v[150:153], v[218:221], v[80:83]
	v_mfma_f32_16x16x32_bf16 v[76:79], v[158:161], v[218:221], v[76:79]
	v_mfma_f32_16x16x32_bf16 v[120:123], v[162:165], v[178:181], v[120:123]
	v_mfma_f32_16x16x32_bf16 v[116:119], v[170:173], v[178:181], v[116:119]
	v_mfma_f32_16x16x32_bf16 v[104:107], v[162:165], v[186:189], v[104:107]
	v_mfma_f32_16x16x32_bf16 v[100:103], v[170:173], v[186:189], v[100:103]
	v_mfma_f32_16x16x32_bf16 v[88:91], v[162:165], v[194:197], v[88:91]
	v_mfma_f32_16x16x32_bf16 v[84:87], v[170:173], v[194:197], v[84:87]
	v_mfma_f32_16x16x32_bf16 v[72:75], v[162:165], v[202:205], v[72:75]
	v_mfma_f32_16x16x32_bf16 v[68:71], v[170:173], v[202:205], v[68:71]
	v_mfma_f32_16x16x32_bf16 v[120:123], v[166:169], v[182:185], v[120:123]
	v_mfma_f32_16x16x32_bf16 v[116:119], v[174:177], v[182:185], v[116:119]
	v_mfma_f32_16x16x32_bf16 v[104:107], v[166:169], v[190:193], v[104:107]
	v_mfma_f32_16x16x32_bf16 v[100:103], v[174:177], v[190:193], v[100:103]
	v_mfma_f32_16x16x32_bf16 v[88:91], v[166:169], v[198:201], v[88:91]
	v_mfma_f32_16x16x32_bf16 v[84:87], v[174:177], v[198:201], v[84:87]
	v_mfma_f32_16x16x32_bf16 v[72:75], v[166:169], v[218:221], v[72:75]
	v_mfma_f32_16x16x32_bf16 v[68:71], v[174:177], v[218:221], v[68:71]
	s_barrier
	s_add_i32 s10, s79, s13
	v_lshl_add_u64 v[206:207], v[206:207], 0, s[56:57]
	s_mov_b32 m0, s10
	ds_read_b128 v[178:181], v145 offset:49152
	ds_read_b128 v[182:185], v145 offset:50176
	ds_read_b128 v[186:189], v145 offset:51200
	ds_read_b128 v[190:193], v145 offset:52224
	ds_read_b128 v[194:197], v145 offset:53248
	ds_read_b128 v[198:201], v145 offset:54272
	ds_read_b128 v[202:205], v145 offset:55296
	ds_read_b128 v[218:221], v145 offset:56320
	global_load_lds_dwordx4 v[206:207], off
	s_add_i32 m0, s10, 0x2000
	s_add_u32 s8, s8, 0x40080
	v_lshl_add_u64 v[206:207], v[210:211], 0, s[56:57]
	s_addc_u32 s9, s9, 0
	s_add_i32 s10, s80, s13
	global_load_lds_dwordx4 v[206:207], off
	v_lshl_add_u64 v[206:207], s[8:9], 0, v[136:137]
	s_mov_b32 m0, s10
	s_nop 0
	global_load_lds_dwordx4 v[206:207], off
	v_lshl_add_u64 v[206:207], s[8:9], 0, v[132:133]
	s_add_i32 m0, s10, 0x2000
	s_nop 0
	global_load_lds_dwordx4 v[206:207], off
	v_lshl_add_u64 v[206:207], v[212:213], 0, s[56:57]
	s_mov_b32 m0, s18
	s_nop 0
	global_load_lds_dwordx4 v[206:207], off
	v_lshl_add_u64 v[206:207], v[222:223], 0, s[56:57]
	s_mov_b32 m0, s19
	s_nop 0
	global_load_lds_dwordx4 v[206:207], off
	s_waitcnt vmcnt(8)
	s_waitcnt lgkmcnt(0)
	s_barrier
	s_waitcnt lgkmcnt(0)
	v_mfma_f32_16x16x32_bf16 v[64:67], v[146:149], v[178:181], v[64:67]
	v_mfma_f32_16x16x32_bf16 v[60:63], v[154:157], v[178:181], v[60:63]
	v_mfma_f32_16x16x32_bf16 v[48:51], v[146:149], v[186:189], v[48:51]
	v_mfma_f32_16x16x32_bf16 v[44:47], v[154:157], v[186:189], v[44:47]
	v_mfma_f32_16x16x32_bf16 v[32:35], v[146:149], v[194:197], v[32:35]
	v_mfma_f32_16x16x32_bf16 v[28:31], v[154:157], v[194:197], v[28:31]
	v_mfma_f32_16x16x32_bf16 v[16:19], v[146:149], v[202:205], v[16:19]
	v_mfma_f32_16x16x32_bf16 v[12:15], v[154:157], v[202:205], v[12:15]
	v_mfma_f32_16x16x32_bf16 v[64:67], v[150:153], v[182:185], v[64:67]
	v_mfma_f32_16x16x32_bf16 v[60:63], v[158:161], v[182:185], v[60:63]
	v_mfma_f32_16x16x32_bf16 v[48:51], v[150:153], v[190:193], v[48:51]
	v_mfma_f32_16x16x32_bf16 v[44:47], v[158:161], v[190:193], v[44:47]
	v_mfma_f32_16x16x32_bf16 v[32:35], v[150:153], v[198:201], v[32:35]
	v_mfma_f32_16x16x32_bf16 v[28:31], v[158:161], v[198:201], v[28:31]
	v_mfma_f32_16x16x32_bf16 v[16:19], v[150:153], v[218:221], v[16:19]
	v_mfma_f32_16x16x32_bf16 v[12:15], v[158:161], v[218:221], v[12:15]
	v_mfma_f32_16x16x32_bf16 v[56:59], v[162:165], v[178:181], v[56:59]
	v_mfma_f32_16x16x32_bf16 v[52:55], v[170:173], v[178:181], v[52:55]
	v_mfma_f32_16x16x32_bf16 v[40:43], v[162:165], v[186:189], v[40:43]
	v_mfma_f32_16x16x32_bf16 v[36:39], v[170:173], v[186:189], v[36:39]
	v_mfma_f32_16x16x32_bf16 v[24:27], v[162:165], v[194:197], v[24:27]
	v_mfma_f32_16x16x32_bf16 v[20:23], v[170:173], v[194:197], v[20:23]
	v_mfma_f32_16x16x32_bf16 v[8:11], v[162:165], v[202:205], v[8:11]
	v_mfma_f32_16x16x32_bf16 v[4:7], v[170:173], v[202:205], v[4:7]
	v_mfma_f32_16x16x32_bf16 v[56:59], v[166:169], v[182:185], v[56:59]
	v_mfma_f32_16x16x32_bf16 v[52:55], v[174:177], v[182:185], v[52:55]
	v_mfma_f32_16x16x32_bf16 v[40:43], v[166:169], v[190:193], v[40:43]
	v_mfma_f32_16x16x32_bf16 v[36:39], v[174:177], v[190:193], v[36:39]
	v_mfma_f32_16x16x32_bf16 v[24:27], v[166:169], v[198:201], v[24:27]
	v_mfma_f32_16x16x32_bf16 v[20:23], v[174:177], v[198:201], v[20:23]
	v_mfma_f32_16x16x32_bf16 v[8:11], v[166:169], v[218:221], v[8:11]
	v_mfma_f32_16x16x32_bf16 v[4:7], v[174:177], v[218:221], v[4:7]
	s_add_i32 s24, s24, 2
	s_add_u32 s6, s6, 0x100
	s_addc_u32 s7, s7, 0
	s_cmp_gt_u32 s24, 13
	s_barrier
	s_cbranch_scc0 .LBB0_985
	s_cmpk_lt_u32 s12, 0x100
	s_cbranch_scc0 .LBB0_988
	s_barrier

.LBB0_2100:
	v_add_u32_e32 v148, s61, v150
	ds_read_b128 v[144:147], v148
	ds_read_b128 v[152:155], v148 offset:1024
	ds_read_b128 v[156:159], v148 offset:2048
	ds_read_b128 v[160:163], v148 offset:3072
	v_add_u32_e32 v148, s77, v150
	ds_read_b128 v[164:167], v148
	ds_read_b128 v[168:171], v148 offset:1024
	ds_read_b128 v[172:175], v148 offset:2048
	ds_read_b128 v[176:179], v148 offset:3072
	s_add_u32 s6, s4, 0xfff00080
	s_addc_u32 s7, s5, -1
	s_cmp_eq_u32 s53, 12
	s_cselect_b32 s9, s31, s7
	s_cselect_b32 s8, s51, s6
	s_cselect_b32 s7, s21, s52
	s_cselect_b32 s6, s20, s29
	v_lshl_add_u64 v[148:149], s[4:5], 0, v[140:141]
	s_add_i32 m0, s19, 0xc000
	ds_read_b128 v[180:183], v151
	ds_read_b128 v[184:187], v151 offset:1024
	ds_read_b128 v[188:191], v151 offset:2048
	ds_read_b128 v[192:195], v151 offset:3072
	ds_read_b128 v[196:199], v151 offset:4096
	ds_read_b128 v[200:203], v151 offset:5120
	ds_read_b128 v[204:207], v151 offset:6144
	ds_read_b128 v[210:213], v151 offset:7168
	global_load_lds_dwordx4 v[148:149], off
	v_lshl_add_u64 v[148:149], s[4:5], 0, v[142:143]
	s_add_i32 m0, s19, 0xe000
	s_nop 0
	global_load_lds_dwordx4 v[148:149], off
	s_waitcnt vmcnt(8)
	s_waitcnt lgkmcnt(0)
	s_barrier
	s_waitcnt lgkmcnt(0)
	v_mfma_f32_16x16x32_bf16 v[128:131], v[144:147], v[180:183], v[128:131]
	v_mfma_f32_16x16x32_bf16 v[124:127], v[156:159], v[180:183], v[124:127]
	v_mfma_f32_16x16x32_bf16 v[112:115], v[144:147], v[188:191], v[112:115]
	v_mfma_f32_16x16x32_bf16 v[108:111], v[156:159], v[188:191], v[108:111]
	v_mfma_f32_16x16x32_bf16 v[96:99], v[144:147], v[196:199], v[96:99]
	v_mfma_f32_16x16x32_bf16 v[92:95], v[156:159], v[196:199], v[92:95]
	v_mfma_f32_16x16x32_bf16 v[80:83], v[144:147], v[204:207], v[80:83]
	v_mfma_f32_16x16x32_bf16 v[76:79], v[156:159], v[204:207], v[76:79]
	v_mfma_f32_16x16x32_bf16 v[128:131], v[152:155], v[184:187], v[128:131]
	v_mfma_f32_16x16x32_bf16 v[124:127], v[160:163], v[184:187], v[124:127]
	v_mfma_f32_16x16x32_bf16 v[112:115], v[152:155], v[192:195], v[112:115]
	v_mfma_f32_16x16x32_bf16 v[108:111], v[160:163], v[192:195], v[108:111]
	v_mfma_f32_16x16x32_bf16 v[96:99], v[152:155], v[200:203], v[96:99]
	v_mfma_f32_16x16x32_bf16 v[92:95], v[160:163], v[200:203], v[92:95]
	v_mfma_f32_16x16x32_bf16 v[80:83], v[152:155], v[210:213], v[80:83]
	v_mfma_f32_16x16x32_bf16 v[76:79], v[160:163], v[210:213], v[76:79]
	v_mfma_f32_16x16x32_bf16 v[120:123], v[164:167], v[180:183], v[120:123]
	v_mfma_f32_16x16x32_bf16 v[116:119], v[172:175], v[180:183], v[116:119]
	v_mfma_f32_16x16x32_bf16 v[104:107], v[164:167], v[188:191], v[104:107]
	v_mfma_f32_16x16x32_bf16 v[100:103], v[172:175], v[188:191], v[100:103]
	v_mfma_f32_16x16x32_bf16 v[88:91], v[164:167], v[196:199], v[88:91]
	v_mfma_f32_16x16x32_bf16 v[84:87], v[172:175], v[196:199], v[84:87]
	v_mfma_f32_16x16x32_bf16 v[72:75], v[164:167], v[204:207], v[72:75]
	v_mfma_f32_16x16x32_bf16 v[68:71], v[172:175], v[204:207], v[68:71]
	v_mfma_f32_16x16x32_bf16 v[120:123], v[168:171], v[184:187], v[120:123]
	v_mfma_f32_16x16x32_bf16 v[116:119], v[176:179], v[184:187], v[116:119]
	v_mfma_f32_16x16x32_bf16 v[104:107], v[168:171], v[192:195], v[104:107]
	v_mfma_f32_16x16x32_bf16 v[100:103], v[176:179], v[192:195], v[100:103]
	v_mfma_f32_16x16x32_bf16 v[88:91], v[168:171], v[200:203], v[88:91]
	v_mfma_f32_16x16x32_bf16 v[84:87], v[176:179], v[200:203], v[84:87]
	v_mfma_f32_16x16x32_bf16 v[72:75], v[168:171], v[210:213], v[72:75]
	v_mfma_f32_16x16x32_bf16 v[68:71], v[176:179], v[210:213], v[68:71]
	s_barrier
	s_add_i32 s58, s61, s37
	v_lshl_add_u64 v[148:149], s[6:7], 0, v[136:137]
	s_mov_b32 m0, s58
	ds_read_b128 v[180:183], v151 offset:16384
	ds_read_b128 v[184:187], v151 offset:17408
	ds_read_b128 v[188:191], v151 offset:18432
	ds_read_b128 v[192:195], v151 offset:19456
	ds_read_b128 v[196:199], v151 offset:20480
	ds_read_b128 v[200:203], v151 offset:21504
	ds_read_b128 v[204:207], v151 offset:22528
	ds_read_b128 v[210:213], v151 offset:23552
	global_load_lds_dwordx4 v[148:149], off
	s_add_i32 m0, s58, 0x2000
	s_add_u32 s58, s6, 0x40000
	v_lshl_add_u64 v[218:219], s[6:7], 0, v[132:133]
	s_addc_u32 s59, s7, 0
	s_add_i32 s60, s77, s37
	global_load_lds_dwordx4 v[218:219], off
	v_lshl_add_u64 v[220:221], s[58:59], 0, v[136:137]
	s_mov_b32 m0, s60
	v_lshl_add_u64 v[222:223], s[8:9], 0, v[134:135]
	global_load_lds_dwordx4 v[220:221], off
	v_lshl_add_u64 v[220:221], s[58:59], 0, v[132:133]
	s_add_i32 m0, s60, 0x2000
	s_nop 0
	global_load_lds_dwordx4 v[220:221], off
	v_lshl_add_u64 v[220:221], s[8:9], 0, v[138:139]
	s_mov_b32 m0, s19
	s_nop 0
	global_load_lds_dwordx4 v[220:221], off
	s_mov_b32 m0, s39
	s_nop 0
	global_load_lds_dwordx4 v[222:223], off
	s_waitcnt vmcnt(8)
	s_waitcnt lgkmcnt(0)
	s_barrier
	s_waitcnt lgkmcnt(0)
	v_mfma_f32_16x16x32_bf16 v[64:67], v[144:147], v[180:183], v[64:67]
	v_mfma_f32_16x16x32_bf16 v[60:63], v[156:159], v[180:183], v[60:63]
	v_mfma_f32_16x16x32_bf16 v[48:51], v[144:147], v[188:191], v[48:51]
	v_mfma_f32_16x16x32_bf16 v[44:47], v[156:159], v[188:191], v[44:47]
	v_mfma_f32_16x16x32_bf16 v[32:35], v[144:147], v[196:199], v[32:35]
	v_mfma_f32_16x16x32_bf16 v[28:31], v[156:159], v[196:199], v[28:31]
	v_mfma_f32_16x16x32_bf16 v[16:19], v[144:147], v[204:207], v[16:19]
	v_mfma_f32_16x16x32_bf16 v[12:15], v[156:159], v[204:207], v[12:15]
	v_mfma_f32_16x16x32_bf16 v[64:67], v[152:155], v[184:187], v[64:67]
	v_mfma_f32_16x16x32_bf16 v[60:63], v[160:163], v[184:187], v[60:63]
	v_mfma_f32_16x16x32_bf16 v[48:51], v[152:155], v[192:195], v[48:51]
	v_mfma_f32_16x16x32_bf16 v[44:47], v[160:163], v[192:195], v[44:47]
	v_mfma_f32_16x16x32_bf16 v[32:35], v[152:155], v[200:203], v[32:35]
	v_mfma_f32_16x16x32_bf16 v[28:31], v[160:163], v[200:203], v[28:31]
	v_mfma_f32_16x16x32_bf16 v[16:19], v[152:155], v[210:213], v[16:19]
	v_mfma_f32_16x16x32_bf16 v[12:15], v[160:163], v[210:213], v[12:15]
	v_mfma_f32_16x16x32_bf16 v[56:59], v[164:167], v[180:183], v[56:59]
	v_mfma_f32_16x16x32_bf16 v[52:55], v[172:175], v[180:183], v[52:55]
	v_mfma_f32_16x16x32_bf16 v[40:43], v[164:167], v[188:191], v[40:43]
	v_mfma_f32_16x16x32_bf16 v[36:39], v[172:175], v[188:191], v[36:39]
	v_mfma_f32_16x16x32_bf16 v[24:27], v[164:167], v[196:199], v[24:27]
	v_mfma_f32_16x16x32_bf16 v[20:23], v[172:175], v[196:199], v[20:23]
	v_mfma_f32_16x16x32_bf16 v[8:11], v[164:167], v[204:207], v[8:11]
	v_mfma_f32_16x16x32_bf16 v[4:7], v[172:175], v[204:207], v[4:7]
	v_mfma_f32_16x16x32_bf16 v[56:59], v[168:171], v[184:187], v[56:59]
	v_mfma_f32_16x16x32_bf16 v[52:55], v[176:179], v[184:187], v[52:55]
	v_mfma_f32_16x16x32_bf16 v[40:43], v[168:171], v[192:195], v[40:43]
	v_mfma_f32_16x16x32_bf16 v[36:39], v[176:179], v[192:195], v[36:39]
	v_mfma_f32_16x16x32_bf16 v[24:27], v[168:171], v[200:203], v[24:27]
	v_mfma_f32_16x16x32_bf16 v[20:23], v[176:179], v[200:203], v[20:23]
	v_mfma_f32_16x16x32_bf16 v[8:11], v[168:171], v[210:213], v[8:11]
	v_mfma_f32_16x16x32_bf16 v[4:7], v[176:179], v[210:213], v[4:7]
	s_barrier
	v_add_u32_e32 v160, s79, v150
	v_add_u32_e32 v176, s80, v150
	ds_read_b128 v[144:147], v160
	ds_read_b128 v[152:155], v160 offset:1024
	ds_read_b128 v[156:159], v160 offset:2048
	ds_read_b128 v[160:163], v160 offset:3072
	ds_read_b128 v[164:167], v176
	ds_read_b128 v[168:171], v176 offset:1024
	ds_read_b128 v[172:175], v176 offset:2048
	ds_read_b128 v[176:179], v176 offset:3072
	s_add_u32 s8, s8, 0x100000
	s_addc_u32 s9, s9, 0
	s_mov_b32 m0, s40
	v_lshl_add_u64 v[224:225], s[8:9], 0, v[138:139]
	ds_read_b128 v[180:183], v151 offset:32768
	ds_read_b128 v[184:187], v151 offset:33792
	ds_read_b128 v[188:191], v151 offset:34816
	ds_read_b128 v[192:195], v151 offset:35840
	ds_read_b128 v[196:199], v151 offset:36864
	ds_read_b128 v[200:203], v151 offset:37888
	ds_read_b128 v[204:207], v151 offset:38912
	ds_read_b128 v[210:213], v151 offset:39936
	global_load_lds_dwordx4 v[224:225], off
	v_lshl_add_u64 v[224:225], s[8:9], 0, v[134:135]
	s_mov_b32 m0, s41
	s_nop 0
	global_load_lds_dwordx4 v[224:225], off
	s_waitcnt vmcnt(8)
	s_waitcnt lgkmcnt(0)
	s_barrier
	s_waitcnt lgkmcnt(0)
	v_mfma_f32_16x16x32_bf16 v[128:131], v[144:147], v[180:183], v[128:131]
	v_mfma_f32_16x16x32_bf16 v[124:127], v[156:159], v[180:183], v[124:127]
	v_mfma_f32_16x16x32_bf16 v[112:115], v[144:147], v[188:191], v[112:115]
	v_mfma_f32_16x16x32_bf16 v[108:111], v[156:159], v[188:191], v[108:111]
	v_mfma_f32_16x16x32_bf16 v[96:99], v[144:147], v[196:199], v[96:99]
	v_mfma_f32_16x16x32_bf16 v[92:95], v[156:159], v[196:199], v[92:95]
	v_mfma_f32_16x16x32_bf16 v[80:83], v[144:147], v[204:207], v[80:83]
	v_mfma_f32_16x16x32_bf16 v[76:79], v[156:159], v[204:207], v[76:79]
	v_mfma_f32_16x16x32_bf16 v[128:131], v[152:155], v[184:187], v[128:131]
	v_mfma_f32_16x16x32_bf16 v[124:127], v[160:163], v[184:187], v[124:127]
	v_mfma_f32_16x16x32_bf16 v[112:115], v[152:155], v[192:195], v[112:115]
	v_mfma_f32_16x16x32_bf16 v[108:111], v[160:163], v[192:195], v[108:111]
	v_mfma_f32_16x16x32_bf16 v[96:99], v[152:155], v[200:203], v[96:99]
	v_mfma_f32_16x16x32_bf16 v[92:95], v[160:163], v[200:203], v[92:95]
	v_mfma_f32_16x16x32_bf16 v[80:83], v[152:155], v[210:213], v[80:83]
	v_mfma_f32_16x16x32_bf16 v[76:79], v[160:163], v[210:213], v[76:79]
	v_mfma_f32_16x16x32_bf16 v[120:123], v[164:167], v[180:183], v[120:123]
	v_mfma_f32_16x16x32_bf16 v[116:119], v[172:175], v[180:183], v[116:119]
	v_mfma_f32_16x16x32_bf16 v[104:107], v[164:167], v[188:191], v[104:107]
	v_mfma_f32_16x16x32_bf16 v[100:103], v[172:175], v[188:191], v[100:103]
	v_mfma_f32_16x16x32_bf16 v[88:91], v[164:167], v[196:199], v[88:91]
	v_mfma_f32_16x16x32_bf16 v[84:87], v[172:175], v[196:199], v[84:87]
	v_mfma_f32_16x16x32_bf16 v[72:75], v[164:167], v[204:207], v[72:75]
	v_mfma_f32_16x16x32_bf16 v[68:71], v[172:175], v[204:207], v[68:71]
	v_mfma_f32_16x16x32_bf16 v[120:123], v[168:171], v[184:187], v[120:123]
	v_mfma_f32_16x16x32_bf16 v[116:119], v[176:179], v[184:187], v[116:119]
	v_mfma_f32_16x16x32_bf16 v[104:107], v[168:171], v[192:195], v[104:107]
	v_mfma_f32_16x16x32_bf16 v[100:103], v[176:179], v[192:195], v[100:103]
	v_mfma_f32_16x16x32_bf16 v[88:91], v[168:171], v[200:203], v[88:91]
	v_mfma_f32_16x16x32_bf16 v[84:87], v[176:179], v[200:203], v[84:87]
	v_mfma_f32_16x16x32_bf16 v[72:75], v[168:171], v[210:213], v[72:75]
	v_mfma_f32_16x16x32_bf16 v[68:71], v[176:179], v[210:213], v[68:71]
	s_barrier
	s_add_i32 s8, s79, s37
	v_lshl_add_u64 v[148:149], v[148:149], 0, s[56:57]
	s_mov_b32 m0, s8
	ds_read_b128 v[180:183], v151 offset:49152
	ds_read_b128 v[184:187], v151 offset:50176
	ds_read_b128 v[188:191], v151 offset:51200
	ds_read_b128 v[192:195], v151 offset:52224
	ds_read_b128 v[196:199], v151 offset:53248
	ds_read_b128 v[200:203], v151 offset:54272
	ds_read_b128 v[204:207], v151 offset:55296
	ds_read_b128 v[210:213], v151 offset:56320
	global_load_lds_dwordx4 v[148:149], off
	s_add_i32 m0, s8, 0x2000
	s_add_u32 s6, s6, 0x40080
	v_lshl_add_u64 v[148:149], v[218:219], 0, s[56:57]
	s_addc_u32 s7, s7, 0
	s_add_i32 s8, s80, s37
	global_load_lds_dwordx4 v[148:149], off
	v_lshl_add_u64 v[148:149], s[6:7], 0, v[136:137]
	s_mov_b32 m0, s8
	s_nop 0
	global_load_lds_dwordx4 v[148:149], off
	v_lshl_add_u64 v[148:149], s[6:7], 0, v[132:133]
	s_add_i32 m0, s8, 0x2000
	s_nop 0
	global_load_lds_dwordx4 v[148:149], off
	v_lshl_add_u64 v[148:149], v[220:221], 0, s[56:57]
	s_mov_b32 m0, s43
	s_nop 0
	global_load_lds_dwordx4 v[148:149], off
	v_lshl_add_u64 v[148:149], v[222:223], 0, s[56:57]
	s_mov_b32 m0, s44
	s_nop 0
	global_load_lds_dwordx4 v[148:149], off
	s_waitcnt vmcnt(8)
	s_waitcnt lgkmcnt(0)
	s_barrier
	s_waitcnt lgkmcnt(0)
	v_mfma_f32_16x16x32_bf16 v[64:67], v[144:147], v[180:183], v[64:67]
	v_mfma_f32_16x16x32_bf16 v[60:63], v[156:159], v[180:183], v[60:63]
	v_mfma_f32_16x16x32_bf16 v[48:51], v[144:147], v[188:191], v[48:51]
	v_mfma_f32_16x16x32_bf16 v[44:47], v[156:159], v[188:191], v[44:47]
	v_mfma_f32_16x16x32_bf16 v[32:35], v[144:147], v[196:199], v[32:35]
	v_mfma_f32_16x16x32_bf16 v[28:31], v[156:159], v[196:199], v[28:31]
	v_mfma_f32_16x16x32_bf16 v[16:19], v[144:147], v[204:207], v[16:19]
	v_mfma_f32_16x16x32_bf16 v[12:15], v[156:159], v[204:207], v[12:15]
	v_mfma_f32_16x16x32_bf16 v[64:67], v[152:155], v[184:187], v[64:67]
	v_mfma_f32_16x16x32_bf16 v[60:63], v[160:163], v[184:187], v[60:63]
	v_mfma_f32_16x16x32_bf16 v[48:51], v[152:155], v[192:195], v[48:51]
	v_mfma_f32_16x16x32_bf16 v[44:47], v[160:163], v[192:195], v[44:47]
	v_mfma_f32_16x16x32_bf16 v[32:35], v[152:155], v[200:203], v[32:35]
	v_mfma_f32_16x16x32_bf16 v[28:31], v[160:163], v[200:203], v[28:31]
	v_mfma_f32_16x16x32_bf16 v[16:19], v[152:155], v[210:213], v[16:19]
	v_mfma_f32_16x16x32_bf16 v[12:15], v[160:163], v[210:213], v[12:15]
	v_mfma_f32_16x16x32_bf16 v[56:59], v[164:167], v[180:183], v[56:59]
	v_mfma_f32_16x16x32_bf16 v[52:55], v[172:175], v[180:183], v[52:55]
	v_mfma_f32_16x16x32_bf16 v[40:43], v[164:167], v[188:191], v[40:43]
	v_mfma_f32_16x16x32_bf16 v[36:39], v[172:175], v[188:191], v[36:39]
	v_mfma_f32_16x16x32_bf16 v[24:27], v[164:167], v[196:199], v[24:27]
	v_mfma_f32_16x16x32_bf16 v[20:23], v[172:175], v[196:199], v[20:23]
	v_mfma_f32_16x16x32_bf16 v[8:11], v[164:167], v[204:207], v[8:11]
	v_mfma_f32_16x16x32_bf16 v[4:7], v[172:175], v[204:207], v[4:7]
	v_mfma_f32_16x16x32_bf16 v[56:59], v[168:171], v[184:187], v[56:59]
	v_mfma_f32_16x16x32_bf16 v[52:55], v[176:179], v[184:187], v[52:55]
	v_mfma_f32_16x16x32_bf16 v[40:43], v[168:171], v[192:195], v[40:43]
	v_mfma_f32_16x16x32_bf16 v[36:39], v[176:179], v[192:195], v[36:39]
	v_mfma_f32_16x16x32_bf16 v[24:27], v[168:171], v[200:203], v[24:27]
	v_mfma_f32_16x16x32_bf16 v[20:23], v[176:179], v[200:203], v[20:23]
	v_mfma_f32_16x16x32_bf16 v[8:11], v[168:171], v[210:213], v[8:11]
	v_mfma_f32_16x16x32_bf16 v[4:7], v[176:179], v[210:213], v[4:7]
	s_add_i32 s53, s53, 2
	s_add_u32 s4, s4, 0x100
	s_addc_u32 s5, s5, 0
	s_add_u32 s29, s29, 0x100
	s_addc_u32 s52, s52, 0
	s_cmp_gt_u32 s53, 13
	s_barrier
	s_cbranch_scc0 .LBB0_2100
	s_and_b64 vcc, exec, s[26:27]
	s_cbranch_vccz .LBB0_2103
	s_barrier

.LBB0_2189:
	v_add_u32_e32 v2, s61, v151
	ds_read_b128 v[144:147], v2
	ds_read_b128 v[154:157], v2 offset:1024
	ds_read_b128 v[158:161], v2 offset:2048
	ds_read_b128 v[162:165], v2 offset:3072
	v_add_u32_e32 v2, s77, v151
	ds_read_b128 v[166:169], v2
	ds_read_b128 v[170:173], v2 offset:1024
	ds_read_b128 v[174:177], v2 offset:2048
	ds_read_b128 v[178:181], v2 offset:3072
	s_add_u32 s26, s4, 0xfffc0080
	s_addc_u32 s27, s5, -1
	s_cmp_eq_u32 s53, 12
	s_cselect_b32 s29, s25, s27
	s_cselect_b32 s28, s49, s26
	s_cselect_b32 s27, s23, s52
	s_cselect_b32 s26, s50, s51
	v_lshl_add_u64 v[148:149], s[4:5], 0, v[140:141]
	s_add_i32 m0, s13, 0xc000
	ds_read_b128 v[182:185], v152
	ds_read_b128 v[186:189], v152 offset:1024
	ds_read_b128 v[190:193], v152 offset:2048
	ds_read_b128 v[194:197], v152 offset:3072
	ds_read_b128 v[198:201], v152 offset:4096
	ds_read_b128 v[202:205], v152 offset:5120
	ds_read_b128 v[210:213], v152 offset:6144
	ds_read_b128 v[218:221], v152 offset:7168
	global_load_lds_dwordx4 v[148:149], off
	v_lshl_add_u64 v[148:149], s[4:5], 0, v[142:143]
	s_add_i32 m0, s13, 0xe000
	s_nop 0
	global_load_lds_dwordx4 v[148:149], off
	s_waitcnt vmcnt(8)
	s_waitcnt lgkmcnt(0)
	s_barrier
	s_waitcnt lgkmcnt(0)
	v_mfma_f32_16x16x32_bf16 v[128:131], v[144:147], v[182:185], v[128:131]
	v_mfma_f32_16x16x32_bf16 v[124:127], v[158:161], v[182:185], v[124:127]
	v_mfma_f32_16x16x32_bf16 v[112:115], v[144:147], v[190:193], v[112:115]
	v_mfma_f32_16x16x32_bf16 v[108:111], v[158:161], v[190:193], v[108:111]
	v_mfma_f32_16x16x32_bf16 v[96:99], v[144:147], v[198:201], v[96:99]
	v_mfma_f32_16x16x32_bf16 v[92:95], v[158:161], v[198:201], v[92:95]
	v_mfma_f32_16x16x32_bf16 v[80:83], v[144:147], v[210:213], v[80:83]
	v_mfma_f32_16x16x32_bf16 v[76:79], v[158:161], v[210:213], v[76:79]
	v_mfma_f32_16x16x32_bf16 v[128:131], v[154:157], v[186:189], v[128:131]
	v_mfma_f32_16x16x32_bf16 v[124:127], v[162:165], v[186:189], v[124:127]
	v_mfma_f32_16x16x32_bf16 v[112:115], v[154:157], v[194:197], v[112:115]
	v_mfma_f32_16x16x32_bf16 v[108:111], v[162:165], v[194:197], v[108:111]
	v_mfma_f32_16x16x32_bf16 v[96:99], v[154:157], v[202:205], v[96:99]
	v_mfma_f32_16x16x32_bf16 v[92:95], v[162:165], v[202:205], v[92:95]
	v_mfma_f32_16x16x32_bf16 v[80:83], v[154:157], v[218:221], v[80:83]
	v_mfma_f32_16x16x32_bf16 v[76:79], v[162:165], v[218:221], v[76:79]
	v_mfma_f32_16x16x32_bf16 v[120:123], v[166:169], v[182:185], v[120:123]
	v_mfma_f32_16x16x32_bf16 v[116:119], v[174:177], v[182:185], v[116:119]
	v_mfma_f32_16x16x32_bf16 v[104:107], v[166:169], v[190:193], v[104:107]
	v_mfma_f32_16x16x32_bf16 v[100:103], v[174:177], v[190:193], v[100:103]
	v_mfma_f32_16x16x32_bf16 v[88:91], v[166:169], v[198:201], v[88:91]
	v_mfma_f32_16x16x32_bf16 v[84:87], v[174:177], v[198:201], v[84:87]
	v_mfma_f32_16x16x32_bf16 v[72:75], v[166:169], v[210:213], v[72:75]
	v_mfma_f32_16x16x32_bf16 v[68:71], v[174:177], v[210:213], v[68:71]
	v_mfma_f32_16x16x32_bf16 v[120:123], v[170:173], v[186:189], v[120:123]
	v_mfma_f32_16x16x32_bf16 v[116:119], v[178:181], v[186:189], v[116:119]
	v_mfma_f32_16x16x32_bf16 v[104:107], v[170:173], v[194:197], v[104:107]
	v_mfma_f32_16x16x32_bf16 v[100:103], v[178:181], v[194:197], v[100:103]
	v_mfma_f32_16x16x32_bf16 v[88:91], v[170:173], v[202:205], v[88:91]
	v_mfma_f32_16x16x32_bf16 v[84:87], v[178:181], v[202:205], v[84:87]
	v_mfma_f32_16x16x32_bf16 v[72:75], v[170:173], v[218:221], v[72:75]
	v_mfma_f32_16x16x32_bf16 v[68:71], v[178:181], v[218:221], v[68:71]
	s_barrier
	s_add_i32 s58, s61, s35
	v_lshl_add_u64 v[148:149], s[26:27], 0, v[136:137]
	s_mov_b32 m0, s58
	ds_read_b128 v[182:185], v152 offset:16384
	ds_read_b128 v[186:189], v152 offset:17408
	ds_read_b128 v[190:193], v152 offset:18432
	ds_read_b128 v[194:197], v152 offset:19456
	ds_read_b128 v[198:201], v152 offset:20480
	ds_read_b128 v[202:205], v152 offset:21504
	ds_read_b128 v[210:213], v152 offset:22528
	ds_read_b128 v[218:221], v152 offset:23552
	global_load_lds_dwordx4 v[148:149], off
	s_add_i32 m0, s58, 0x2000
	s_add_u32 s58, s26, 0x40000
	v_lshl_add_u64 v[206:207], s[26:27], 0, v[132:133]
	s_addc_u32 s59, s27, 0
	s_add_i32 s60, s77, s35
	global_load_lds_dwordx4 v[206:207], off
	v_lshl_add_u64 v[222:223], s[58:59], 0, v[136:137]
	s_mov_b32 m0, s60
	v_lshl_add_u64 v[224:225], s[28:29], 0, v[134:135]
	global_load_lds_dwordx4 v[222:223], off
	v_lshl_add_u64 v[222:223], s[58:59], 0, v[132:133]
	s_add_i32 m0, s60, 0x2000
	s_nop 0
	global_load_lds_dwordx4 v[222:223], off
	v_lshl_add_u64 v[222:223], s[28:29], 0, v[138:139]
	s_mov_b32 m0, s13
	s_nop 0
	global_load_lds_dwordx4 v[222:223], off
	s_mov_b32 m0, s37
	s_nop 0
	global_load_lds_dwordx4 v[224:225], off
	s_waitcnt vmcnt(8)
	s_waitcnt lgkmcnt(0)
	s_barrier
	s_waitcnt lgkmcnt(0)
	v_mfma_f32_16x16x32_bf16 v[64:67], v[144:147], v[182:185], v[64:67]
	v_mfma_f32_16x16x32_bf16 v[60:63], v[158:161], v[182:185], v[60:63]
	v_mfma_f32_16x16x32_bf16 v[48:51], v[144:147], v[190:193], v[48:51]
	v_mfma_f32_16x16x32_bf16 v[44:47], v[158:161], v[190:193], v[44:47]
	v_mfma_f32_16x16x32_bf16 v[32:35], v[144:147], v[198:201], v[32:35]
	v_mfma_f32_16x16x32_bf16 v[28:31], v[158:161], v[198:201], v[28:31]
	v_mfma_f32_16x16x32_bf16 v[16:19], v[144:147], v[210:213], v[16:19]
	v_mfma_f32_16x16x32_bf16 v[12:15], v[158:161], v[210:213], v[12:15]
	v_mfma_f32_16x16x32_bf16 v[64:67], v[154:157], v[186:189], v[64:67]
	v_mfma_f32_16x16x32_bf16 v[60:63], v[162:165], v[186:189], v[60:63]
	v_mfma_f32_16x16x32_bf16 v[48:51], v[154:157], v[194:197], v[48:51]
	v_mfma_f32_16x16x32_bf16 v[44:47], v[162:165], v[194:197], v[44:47]
	v_mfma_f32_16x16x32_bf16 v[32:35], v[154:157], v[202:205], v[32:35]
	v_mfma_f32_16x16x32_bf16 v[28:31], v[162:165], v[202:205], v[28:31]
	v_mfma_f32_16x16x32_bf16 v[16:19], v[154:157], v[218:221], v[16:19]
	v_mfma_f32_16x16x32_bf16 v[12:15], v[162:165], v[218:221], v[12:15]
	v_mfma_f32_16x16x32_bf16 v[56:59], v[166:169], v[182:185], v[56:59]
	v_mfma_f32_16x16x32_bf16 v[52:55], v[174:177], v[182:185], v[52:55]
	v_mfma_f32_16x16x32_bf16 v[40:43], v[166:169], v[190:193], v[40:43]
	v_mfma_f32_16x16x32_bf16 v[36:39], v[174:177], v[190:193], v[36:39]
	v_mfma_f32_16x16x32_bf16 v[24:27], v[166:169], v[198:201], v[24:27]
	v_mfma_f32_16x16x32_bf16 v[20:23], v[174:177], v[198:201], v[20:23]
	v_mfma_f32_16x16x32_bf16 v[8:11], v[166:169], v[210:213], v[8:11]
	v_mfma_f32_16x16x32_bf16 v[4:7], v[174:177], v[210:213], v[4:7]
	v_mfma_f32_16x16x32_bf16 v[56:59], v[170:173], v[186:189], v[56:59]
	v_mfma_f32_16x16x32_bf16 v[52:55], v[178:181], v[186:189], v[52:55]
	v_mfma_f32_16x16x32_bf16 v[40:43], v[170:173], v[194:197], v[40:43]
	v_mfma_f32_16x16x32_bf16 v[36:39], v[178:181], v[194:197], v[36:39]
	v_mfma_f32_16x16x32_bf16 v[24:27], v[170:173], v[202:205], v[24:27]
	v_mfma_f32_16x16x32_bf16 v[20:23], v[178:181], v[202:205], v[20:23]
	v_mfma_f32_16x16x32_bf16 v[8:11], v[170:173], v[218:221], v[8:11]
	v_mfma_f32_16x16x32_bf16 v[4:7], v[178:181], v[218:221], v[4:7]
	s_barrier
	v_add_u32_e32 v2, s79, v151
	ds_read_b128 v[144:147], v2
	ds_read_b128 v[154:157], v2 offset:1024
	ds_read_b128 v[158:161], v2 offset:2048
	ds_read_b128 v[162:165], v2 offset:3072
	v_add_u32_e32 v2, s80, v151
	ds_read_b128 v[166:169], v2
	ds_read_b128 v[170:173], v2 offset:1024
	ds_read_b128 v[174:177], v2 offset:2048
	ds_read_b128 v[178:181], v2 offset:3072
	s_add_u32 s28, s28, 0x40000
	s_addc_u32 s29, s29, 0
	s_mov_b32 m0, s38
	v_lshl_add_u64 v[226:227], s[28:29], 0, v[138:139]
	ds_read_b128 v[182:185], v152 offset:32768
	ds_read_b128 v[186:189], v152 offset:33792
	ds_read_b128 v[190:193], v152 offset:34816
	ds_read_b128 v[194:197], v152 offset:35840
	ds_read_b128 v[198:201], v152 offset:36864
	ds_read_b128 v[202:205], v152 offset:37888
	ds_read_b128 v[210:213], v152 offset:38912
	ds_read_b128 v[218:221], v152 offset:39936
	global_load_lds_dwordx4 v[226:227], off
	v_lshl_add_u64 v[226:227], s[28:29], 0, v[134:135]
	s_mov_b32 m0, s39
	s_nop 0
	global_load_lds_dwordx4 v[226:227], off
	s_waitcnt vmcnt(8)
	s_waitcnt lgkmcnt(0)
	s_barrier
	s_waitcnt lgkmcnt(0)
	v_mfma_f32_16x16x32_bf16 v[128:131], v[144:147], v[182:185], v[128:131]
	v_mfma_f32_16x16x32_bf16 v[124:127], v[158:161], v[182:185], v[124:127]
	v_mfma_f32_16x16x32_bf16 v[112:115], v[144:147], v[190:193], v[112:115]
	v_mfma_f32_16x16x32_bf16 v[108:111], v[158:161], v[190:193], v[108:111]
	v_mfma_f32_16x16x32_bf16 v[96:99], v[144:147], v[198:201], v[96:99]
	v_mfma_f32_16x16x32_bf16 v[92:95], v[158:161], v[198:201], v[92:95]
	v_mfma_f32_16x16x32_bf16 v[80:83], v[144:147], v[210:213], v[80:83]
	v_mfma_f32_16x16x32_bf16 v[76:79], v[158:161], v[210:213], v[76:79]
	v_mfma_f32_16x16x32_bf16 v[128:131], v[154:157], v[186:189], v[128:131]
	v_mfma_f32_16x16x32_bf16 v[124:127], v[162:165], v[186:189], v[124:127]
	v_mfma_f32_16x16x32_bf16 v[112:115], v[154:157], v[194:197], v[112:115]
	v_mfma_f32_16x16x32_bf16 v[108:111], v[162:165], v[194:197], v[108:111]
	v_mfma_f32_16x16x32_bf16 v[96:99], v[154:157], v[202:205], v[96:99]
	v_mfma_f32_16x16x32_bf16 v[92:95], v[162:165], v[202:205], v[92:95]
	v_mfma_f32_16x16x32_bf16 v[80:83], v[154:157], v[218:221], v[80:83]
	v_mfma_f32_16x16x32_bf16 v[76:79], v[162:165], v[218:221], v[76:79]
	v_mfma_f32_16x16x32_bf16 v[120:123], v[166:169], v[182:185], v[120:123]
	v_mfma_f32_16x16x32_bf16 v[116:119], v[174:177], v[182:185], v[116:119]
	v_mfma_f32_16x16x32_bf16 v[104:107], v[166:169], v[190:193], v[104:107]
	v_mfma_f32_16x16x32_bf16 v[100:103], v[174:177], v[190:193], v[100:103]
	v_mfma_f32_16x16x32_bf16 v[88:91], v[166:169], v[198:201], v[88:91]
	v_mfma_f32_16x16x32_bf16 v[84:87], v[174:177], v[198:201], v[84:87]
	v_mfma_f32_16x16x32_bf16 v[72:75], v[166:169], v[210:213], v[72:75]
	v_mfma_f32_16x16x32_bf16 v[68:71], v[174:177], v[210:213], v[68:71]
	v_mfma_f32_16x16x32_bf16 v[120:123], v[170:173], v[186:189], v[120:123]
	v_mfma_f32_16x16x32_bf16 v[116:119], v[178:181], v[186:189], v[116:119]
	v_mfma_f32_16x16x32_bf16 v[104:107], v[170:173], v[194:197], v[104:107]
	v_mfma_f32_16x16x32_bf16 v[100:103], v[178:181], v[194:197], v[100:103]
	v_mfma_f32_16x16x32_bf16 v[88:91], v[170:173], v[202:205], v[88:91]
	v_mfma_f32_16x16x32_bf16 v[84:87], v[178:181], v[202:205], v[84:87]
	v_mfma_f32_16x16x32_bf16 v[72:75], v[170:173], v[218:221], v[72:75]
	v_mfma_f32_16x16x32_bf16 v[68:71], v[178:181], v[218:221], v[68:71]
	s_barrier
	s_add_i32 s28, s79, s35
	v_lshl_add_u64 v[148:149], v[148:149], 0, s[56:57]
	s_mov_b32 m0, s28
	ds_read_b128 v[182:185], v152 offset:49152
	ds_read_b128 v[186:189], v152 offset:50176
	ds_read_b128 v[190:193], v152 offset:51200
	ds_read_b128 v[194:197], v152 offset:52224
	ds_read_b128 v[198:201], v152 offset:53248
	ds_read_b128 v[202:205], v152 offset:54272
	ds_read_b128 v[210:213], v152 offset:55296
	ds_read_b128 v[218:221], v152 offset:56320
	global_load_lds_dwordx4 v[148:149], off
	s_add_i32 m0, s28, 0x2000
	s_add_u32 s26, s26, 0x40080
	v_lshl_add_u64 v[148:149], v[206:207], 0, s[56:57]
	s_addc_u32 s27, s27, 0
	s_add_i32 s28, s80, s35
	global_load_lds_dwordx4 v[148:149], off
	v_lshl_add_u64 v[148:149], s[26:27], 0, v[136:137]
	s_mov_b32 m0, s28
	s_nop 0
	global_load_lds_dwordx4 v[148:149], off
	v_lshl_add_u64 v[148:149], s[26:27], 0, v[132:133]
	s_add_i32 m0, s28, 0x2000
	s_nop 0
	global_load_lds_dwordx4 v[148:149], off
	v_lshl_add_u64 v[148:149], v[222:223], 0, s[56:57]
	s_mov_b32 m0, s41
	s_nop 0
	global_load_lds_dwordx4 v[148:149], off
	v_lshl_add_u64 v[148:149], v[224:225], 0, s[56:57]
	s_mov_b32 m0, s42
	s_nop 0
	global_load_lds_dwordx4 v[148:149], off
	s_waitcnt vmcnt(8)
	s_waitcnt lgkmcnt(0)
	s_barrier
	s_waitcnt lgkmcnt(0)
	v_mfma_f32_16x16x32_bf16 v[64:67], v[144:147], v[182:185], v[64:67]
	v_mfma_f32_16x16x32_bf16 v[60:63], v[158:161], v[182:185], v[60:63]
	v_mfma_f32_16x16x32_bf16 v[48:51], v[144:147], v[190:193], v[48:51]
	v_mfma_f32_16x16x32_bf16 v[44:47], v[158:161], v[190:193], v[44:47]
	v_mfma_f32_16x16x32_bf16 v[32:35], v[144:147], v[198:201], v[32:35]
	v_mfma_f32_16x16x32_bf16 v[28:31], v[158:161], v[198:201], v[28:31]
	v_mfma_f32_16x16x32_bf16 v[16:19], v[144:147], v[210:213], v[16:19]
	v_mfma_f32_16x16x32_bf16 v[12:15], v[158:161], v[210:213], v[12:15]
	v_mfma_f32_16x16x32_bf16 v[64:67], v[154:157], v[186:189], v[64:67]
	v_mfma_f32_16x16x32_bf16 v[60:63], v[162:165], v[186:189], v[60:63]
	v_mfma_f32_16x16x32_bf16 v[48:51], v[154:157], v[194:197], v[48:51]
	v_mfma_f32_16x16x32_bf16 v[44:47], v[162:165], v[194:197], v[44:47]
	v_mfma_f32_16x16x32_bf16 v[32:35], v[154:157], v[202:205], v[32:35]
	v_mfma_f32_16x16x32_bf16 v[28:31], v[162:165], v[202:205], v[28:31]
	v_mfma_f32_16x16x32_bf16 v[16:19], v[154:157], v[218:221], v[16:19]
	v_mfma_f32_16x16x32_bf16 v[12:15], v[162:165], v[218:221], v[12:15]
	v_mfma_f32_16x16x32_bf16 v[56:59], v[166:169], v[182:185], v[56:59]
	v_mfma_f32_16x16x32_bf16 v[52:55], v[174:177], v[182:185], v[52:55]
	v_mfma_f32_16x16x32_bf16 v[40:43], v[166:169], v[190:193], v[40:43]
	v_mfma_f32_16x16x32_bf16 v[36:39], v[174:177], v[190:193], v[36:39]
	v_mfma_f32_16x16x32_bf16 v[24:27], v[166:169], v[198:201], v[24:27]
	v_mfma_f32_16x16x32_bf16 v[20:23], v[174:177], v[198:201], v[20:23]
	v_mfma_f32_16x16x32_bf16 v[8:11], v[166:169], v[210:213], v[8:11]
	v_mfma_f32_16x16x32_bf16 v[4:7], v[174:177], v[210:213], v[4:7]
	v_mfma_f32_16x16x32_bf16 v[56:59], v[170:173], v[186:189], v[56:59]
	v_mfma_f32_16x16x32_bf16 v[52:55], v[178:181], v[186:189], v[52:55]
	v_mfma_f32_16x16x32_bf16 v[40:43], v[170:173], v[194:197], v[40:43]
	v_mfma_f32_16x16x32_bf16 v[36:39], v[178:181], v[194:197], v[36:39]
	v_mfma_f32_16x16x32_bf16 v[24:27], v[170:173], v[202:205], v[24:27]
	v_mfma_f32_16x16x32_bf16 v[20:23], v[178:181], v[202:205], v[20:23]
	v_mfma_f32_16x16x32_bf16 v[8:11], v[170:173], v[218:221], v[8:11]
	v_mfma_f32_16x16x32_bf16 v[4:7], v[178:181], v[218:221], v[4:7]
	s_add_i32 s53, s53, 2
	s_add_u32 s4, s4, 0x100
	s_addc_u32 s5, s5, 0
	s_add_u32 s51, s51, 0x100
	s_addc_u32 s52, s52, 0
	s_cmp_gt_u32 s53, 13
	s_barrier
	s_cbranch_scc0 .LBB0_2189
	s_and_b64 vcc, exec, s[20:21]
	s_cbranch_vccz .LBB0_2192
	s_barrier

.LBB0_2540:
	v_add_u32_e32 v2, s61, v151
	ds_read_b128 v[144:147], v2
	ds_read_b128 v[154:157], v2 offset:1024
	ds_read_b128 v[158:161], v2 offset:2048
	ds_read_b128 v[162:165], v2 offset:3072
	v_add_u32_e32 v2, s77, v151
	ds_read_b128 v[166:169], v2
	ds_read_b128 v[170:173], v2 offset:1024
	ds_read_b128 v[174:177], v2 offset:2048
	ds_read_b128 v[178:181], v2 offset:3072
	s_add_u32 s26, s4, 0xfffc0080
	s_addc_u32 s27, s5, -1
	s_cmp_eq_u32 s53, 12
	s_cselect_b32 s29, s19, s27
	s_cselect_b32 s28, s49, s26
	s_cselect_b32 s27, s21, s52
	s_cselect_b32 s26, s50, s51
	v_lshl_add_u64 v[148:149], s[4:5], 0, v[140:141]
	s_add_i32 m0, s13, 0xc000
	ds_read_b128 v[182:185], v152
	ds_read_b128 v[186:189], v152 offset:1024
	ds_read_b128 v[190:193], v152 offset:2048
	ds_read_b128 v[194:197], v152 offset:3072
	ds_read_b128 v[198:201], v152 offset:4096
	ds_read_b128 v[202:205], v152 offset:5120
	ds_read_b128 v[210:213], v152 offset:6144
	ds_read_b128 v[218:221], v152 offset:7168
	global_load_lds_dwordx4 v[148:149], off
	v_lshl_add_u64 v[148:149], s[4:5], 0, v[142:143]
	s_add_i32 m0, s13, 0xe000
	s_nop 0
	global_load_lds_dwordx4 v[148:149], off
	s_waitcnt vmcnt(8)
	s_waitcnt lgkmcnt(0)
	s_barrier
	s_waitcnt lgkmcnt(0)
	v_mfma_f32_16x16x32_bf16 v[128:131], v[144:147], v[182:185], v[128:131]
	v_mfma_f32_16x16x32_bf16 v[124:127], v[158:161], v[182:185], v[124:127]
	v_mfma_f32_16x16x32_bf16 v[112:115], v[144:147], v[190:193], v[112:115]
	v_mfma_f32_16x16x32_bf16 v[108:111], v[158:161], v[190:193], v[108:111]
	v_mfma_f32_16x16x32_bf16 v[96:99], v[144:147], v[198:201], v[96:99]
	v_mfma_f32_16x16x32_bf16 v[92:95], v[158:161], v[198:201], v[92:95]
	v_mfma_f32_16x16x32_bf16 v[80:83], v[144:147], v[210:213], v[80:83]
	v_mfma_f32_16x16x32_bf16 v[76:79], v[158:161], v[210:213], v[76:79]
	v_mfma_f32_16x16x32_bf16 v[128:131], v[154:157], v[186:189], v[128:131]
	v_mfma_f32_16x16x32_bf16 v[124:127], v[162:165], v[186:189], v[124:127]
	v_mfma_f32_16x16x32_bf16 v[112:115], v[154:157], v[194:197], v[112:115]
	v_mfma_f32_16x16x32_bf16 v[108:111], v[162:165], v[194:197], v[108:111]
	v_mfma_f32_16x16x32_bf16 v[96:99], v[154:157], v[202:205], v[96:99]
	v_mfma_f32_16x16x32_bf16 v[92:95], v[162:165], v[202:205], v[92:95]
	v_mfma_f32_16x16x32_bf16 v[80:83], v[154:157], v[218:221], v[80:83]
	v_mfma_f32_16x16x32_bf16 v[76:79], v[162:165], v[218:221], v[76:79]
	v_mfma_f32_16x16x32_bf16 v[120:123], v[166:169], v[182:185], v[120:123]
	v_mfma_f32_16x16x32_bf16 v[116:119], v[174:177], v[182:185], v[116:119]
	v_mfma_f32_16x16x32_bf16 v[104:107], v[166:169], v[190:193], v[104:107]
	v_mfma_f32_16x16x32_bf16 v[100:103], v[174:177], v[190:193], v[100:103]
	v_mfma_f32_16x16x32_bf16 v[88:91], v[166:169], v[198:201], v[88:91]
	v_mfma_f32_16x16x32_bf16 v[84:87], v[174:177], v[198:201], v[84:87]
	v_mfma_f32_16x16x32_bf16 v[72:75], v[166:169], v[210:213], v[72:75]
	v_mfma_f32_16x16x32_bf16 v[68:71], v[174:177], v[210:213], v[68:71]
	v_mfma_f32_16x16x32_bf16 v[120:123], v[170:173], v[186:189], v[120:123]
	v_mfma_f32_16x16x32_bf16 v[116:119], v[178:181], v[186:189], v[116:119]
	v_mfma_f32_16x16x32_bf16 v[104:107], v[170:173], v[194:197], v[104:107]
	v_mfma_f32_16x16x32_bf16 v[100:103], v[178:181], v[194:197], v[100:103]
	v_mfma_f32_16x16x32_bf16 v[88:91], v[170:173], v[202:205], v[88:91]
	v_mfma_f32_16x16x32_bf16 v[84:87], v[178:181], v[202:205], v[84:87]
	v_mfma_f32_16x16x32_bf16 v[72:75], v[170:173], v[218:221], v[72:75]
	v_mfma_f32_16x16x32_bf16 v[68:71], v[178:181], v[218:221], v[68:71]
	s_barrier
	s_add_i32 s58, s61, s35
	v_lshl_add_u64 v[148:149], s[26:27], 0, v[136:137]
	s_mov_b32 m0, s58
	ds_read_b128 v[182:185], v152 offset:16384
	ds_read_b128 v[186:189], v152 offset:17408
	ds_read_b128 v[190:193], v152 offset:18432
	ds_read_b128 v[194:197], v152 offset:19456
	ds_read_b128 v[198:201], v152 offset:20480
	ds_read_b128 v[202:205], v152 offset:21504
	ds_read_b128 v[210:213], v152 offset:22528
	ds_read_b128 v[218:221], v152 offset:23552
	global_load_lds_dwordx4 v[148:149], off
	s_add_i32 m0, s58, 0x2000
	s_add_u32 s58, s26, 0x40000
	v_lshl_add_u64 v[206:207], s[26:27], 0, v[132:133]
	s_addc_u32 s59, s27, 0
	s_add_i32 s60, s77, s35
	global_load_lds_dwordx4 v[206:207], off
	v_lshl_add_u64 v[222:223], s[58:59], 0, v[136:137]
	s_mov_b32 m0, s60
	v_lshl_add_u64 v[224:225], s[28:29], 0, v[134:135]
	global_load_lds_dwordx4 v[222:223], off
	v_lshl_add_u64 v[222:223], s[58:59], 0, v[132:133]
	s_add_i32 m0, s60, 0x2000
	s_nop 0
	global_load_lds_dwordx4 v[222:223], off
	v_lshl_add_u64 v[222:223], s[28:29], 0, v[138:139]
	s_mov_b32 m0, s13
	s_nop 0
	global_load_lds_dwordx4 v[222:223], off
	s_mov_b32 m0, s36
	s_nop 0
	global_load_lds_dwordx4 v[224:225], off
	s_waitcnt vmcnt(8)
	s_waitcnt lgkmcnt(0)
	s_barrier
	s_waitcnt lgkmcnt(0)
	v_mfma_f32_16x16x32_bf16 v[64:67], v[144:147], v[182:185], v[64:67]
	v_mfma_f32_16x16x32_bf16 v[60:63], v[158:161], v[182:185], v[60:63]
	v_mfma_f32_16x16x32_bf16 v[48:51], v[144:147], v[190:193], v[48:51]
	v_mfma_f32_16x16x32_bf16 v[44:47], v[158:161], v[190:193], v[44:47]
	v_mfma_f32_16x16x32_bf16 v[32:35], v[144:147], v[198:201], v[32:35]
	v_mfma_f32_16x16x32_bf16 v[28:31], v[158:161], v[198:201], v[28:31]
	v_mfma_f32_16x16x32_bf16 v[16:19], v[144:147], v[210:213], v[16:19]
	v_mfma_f32_16x16x32_bf16 v[12:15], v[158:161], v[210:213], v[12:15]
	v_mfma_f32_16x16x32_bf16 v[64:67], v[154:157], v[186:189], v[64:67]
	v_mfma_f32_16x16x32_bf16 v[60:63], v[162:165], v[186:189], v[60:63]
	v_mfma_f32_16x16x32_bf16 v[48:51], v[154:157], v[194:197], v[48:51]
	v_mfma_f32_16x16x32_bf16 v[44:47], v[162:165], v[194:197], v[44:47]
	v_mfma_f32_16x16x32_bf16 v[32:35], v[154:157], v[202:205], v[32:35]
	v_mfma_f32_16x16x32_bf16 v[28:31], v[162:165], v[202:205], v[28:31]
	v_mfma_f32_16x16x32_bf16 v[16:19], v[154:157], v[218:221], v[16:19]
	v_mfma_f32_16x16x32_bf16 v[12:15], v[162:165], v[218:221], v[12:15]
	v_mfma_f32_16x16x32_bf16 v[56:59], v[166:169], v[182:185], v[56:59]
	v_mfma_f32_16x16x32_bf16 v[52:55], v[174:177], v[182:185], v[52:55]
	v_mfma_f32_16x16x32_bf16 v[40:43], v[166:169], v[190:193], v[40:43]
	v_mfma_f32_16x16x32_bf16 v[36:39], v[174:177], v[190:193], v[36:39]
	v_mfma_f32_16x16x32_bf16 v[24:27], v[166:169], v[198:201], v[24:27]
	v_mfma_f32_16x16x32_bf16 v[20:23], v[174:177], v[198:201], v[20:23]
	v_mfma_f32_16x16x32_bf16 v[8:11], v[166:169], v[210:213], v[8:11]
	v_mfma_f32_16x16x32_bf16 v[4:7], v[174:177], v[210:213], v[4:7]
	v_mfma_f32_16x16x32_bf16 v[56:59], v[170:173], v[186:189], v[56:59]
	v_mfma_f32_16x16x32_bf16 v[52:55], v[178:181], v[186:189], v[52:55]
	v_mfma_f32_16x16x32_bf16 v[40:43], v[170:173], v[194:197], v[40:43]
	v_mfma_f32_16x16x32_bf16 v[36:39], v[178:181], v[194:197], v[36:39]
	v_mfma_f32_16x16x32_bf16 v[24:27], v[170:173], v[202:205], v[24:27]
	v_mfma_f32_16x16x32_bf16 v[20:23], v[178:181], v[202:205], v[20:23]
	v_mfma_f32_16x16x32_bf16 v[8:11], v[170:173], v[218:221], v[8:11]
	v_mfma_f32_16x16x32_bf16 v[4:7], v[178:181], v[218:221], v[4:7]
	s_barrier
	v_add_u32_e32 v2, s79, v151
	ds_read_b128 v[144:147], v2
	ds_read_b128 v[154:157], v2 offset:1024
	ds_read_b128 v[158:161], v2 offset:2048
	ds_read_b128 v[162:165], v2 offset:3072
	v_add_u32_e32 v2, s80, v151
	ds_read_b128 v[166:169], v2
	ds_read_b128 v[170:173], v2 offset:1024
	ds_read_b128 v[174:177], v2 offset:2048
	ds_read_b128 v[178:181], v2 offset:3072
	s_add_u32 s28, s28, 0x40000
	s_addc_u32 s29, s29, 0
	s_mov_b32 m0, s37
	v_lshl_add_u64 v[226:227], s[28:29], 0, v[138:139]
	ds_read_b128 v[182:185], v152 offset:32768
	ds_read_b128 v[186:189], v152 offset:33792
	ds_read_b128 v[190:193], v152 offset:34816
	ds_read_b128 v[194:197], v152 offset:35840
	ds_read_b128 v[198:201], v152 offset:36864
	ds_read_b128 v[202:205], v152 offset:37888
	ds_read_b128 v[210:213], v152 offset:38912
	ds_read_b128 v[218:221], v152 offset:39936
	global_load_lds_dwordx4 v[226:227], off
	v_lshl_add_u64 v[226:227], s[28:29], 0, v[134:135]
	s_mov_b32 m0, s38
	s_nop 0
	global_load_lds_dwordx4 v[226:227], off
	s_waitcnt vmcnt(8)
	s_waitcnt lgkmcnt(0)
	s_barrier
	s_waitcnt lgkmcnt(0)
	v_mfma_f32_16x16x32_bf16 v[128:131], v[144:147], v[182:185], v[128:131]
	v_mfma_f32_16x16x32_bf16 v[124:127], v[158:161], v[182:185], v[124:127]
	v_mfma_f32_16x16x32_bf16 v[112:115], v[144:147], v[190:193], v[112:115]
	v_mfma_f32_16x16x32_bf16 v[108:111], v[158:161], v[190:193], v[108:111]
	v_mfma_f32_16x16x32_bf16 v[96:99], v[144:147], v[198:201], v[96:99]
	v_mfma_f32_16x16x32_bf16 v[92:95], v[158:161], v[198:201], v[92:95]
	v_mfma_f32_16x16x32_bf16 v[80:83], v[144:147], v[210:213], v[80:83]
	v_mfma_f32_16x16x32_bf16 v[76:79], v[158:161], v[210:213], v[76:79]
	v_mfma_f32_16x16x32_bf16 v[128:131], v[154:157], v[186:189], v[128:131]
	v_mfma_f32_16x16x32_bf16 v[124:127], v[162:165], v[186:189], v[124:127]
	v_mfma_f32_16x16x32_bf16 v[112:115], v[154:157], v[194:197], v[112:115]
	v_mfma_f32_16x16x32_bf16 v[108:111], v[162:165], v[194:197], v[108:111]
	v_mfma_f32_16x16x32_bf16 v[96:99], v[154:157], v[202:205], v[96:99]
	v_mfma_f32_16x16x32_bf16 v[92:95], v[162:165], v[202:205], v[92:95]
	v_mfma_f32_16x16x32_bf16 v[80:83], v[154:157], v[218:221], v[80:83]
	v_mfma_f32_16x16x32_bf16 v[76:79], v[162:165], v[218:221], v[76:79]
	v_mfma_f32_16x16x32_bf16 v[120:123], v[166:169], v[182:185], v[120:123]
	v_mfma_f32_16x16x32_bf16 v[116:119], v[174:177], v[182:185], v[116:119]
	v_mfma_f32_16x16x32_bf16 v[104:107], v[166:169], v[190:193], v[104:107]
	v_mfma_f32_16x16x32_bf16 v[100:103], v[174:177], v[190:193], v[100:103]
	v_mfma_f32_16x16x32_bf16 v[88:91], v[166:169], v[198:201], v[88:91]
	v_mfma_f32_16x16x32_bf16 v[84:87], v[174:177], v[198:201], v[84:87]
	v_mfma_f32_16x16x32_bf16 v[72:75], v[166:169], v[210:213], v[72:75]
	v_mfma_f32_16x16x32_bf16 v[68:71], v[174:177], v[210:213], v[68:71]
	v_mfma_f32_16x16x32_bf16 v[120:123], v[170:173], v[186:189], v[120:123]
	v_mfma_f32_16x16x32_bf16 v[116:119], v[178:181], v[186:189], v[116:119]
	v_mfma_f32_16x16x32_bf16 v[104:107], v[170:173], v[194:197], v[104:107]
	v_mfma_f32_16x16x32_bf16 v[100:103], v[178:181], v[194:197], v[100:103]
	v_mfma_f32_16x16x32_bf16 v[88:91], v[170:173], v[202:205], v[88:91]
	v_mfma_f32_16x16x32_bf16 v[84:87], v[178:181], v[202:205], v[84:87]
	v_mfma_f32_16x16x32_bf16 v[72:75], v[170:173], v[218:221], v[72:75]
	v_mfma_f32_16x16x32_bf16 v[68:71], v[178:181], v[218:221], v[68:71]
	s_barrier
	s_add_i32 s28, s79, s35
	v_lshl_add_u64 v[148:149], v[148:149], 0, s[56:57]
	s_mov_b32 m0, s28
	ds_read_b128 v[182:185], v152 offset:49152
	ds_read_b128 v[186:189], v152 offset:50176
	ds_read_b128 v[190:193], v152 offset:51200
	ds_read_b128 v[194:197], v152 offset:52224
	ds_read_b128 v[198:201], v152 offset:53248
	ds_read_b128 v[202:205], v152 offset:54272
	ds_read_b128 v[210:213], v152 offset:55296
	ds_read_b128 v[218:221], v152 offset:56320
	global_load_lds_dwordx4 v[148:149], off
	s_add_i32 m0, s28, 0x2000
	s_add_u32 s26, s26, 0x40080
	v_lshl_add_u64 v[148:149], v[206:207], 0, s[56:57]
	s_addc_u32 s27, s27, 0
	s_add_i32 s28, s80, s35
	global_load_lds_dwordx4 v[148:149], off
	v_lshl_add_u64 v[148:149], s[26:27], 0, v[136:137]
	s_mov_b32 m0, s28
	s_nop 0
	global_load_lds_dwordx4 v[148:149], off
	v_lshl_add_u64 v[148:149], s[26:27], 0, v[132:133]
	s_add_i32 m0, s28, 0x2000
	s_nop 0
	global_load_lds_dwordx4 v[148:149], off
	v_lshl_add_u64 v[148:149], v[222:223], 0, s[56:57]
	s_mov_b32 m0, s41
	s_nop 0
	global_load_lds_dwordx4 v[148:149], off
	v_lshl_add_u64 v[148:149], v[224:225], 0, s[56:57]
	s_mov_b32 m0, s42
	s_nop 0
	global_load_lds_dwordx4 v[148:149], off
	s_waitcnt vmcnt(8)
	s_waitcnt lgkmcnt(0)
	s_barrier
	s_waitcnt lgkmcnt(0)
	v_mfma_f32_16x16x32_bf16 v[64:67], v[144:147], v[182:185], v[64:67]
	v_mfma_f32_16x16x32_bf16 v[60:63], v[158:161], v[182:185], v[60:63]
	v_mfma_f32_16x16x32_bf16 v[48:51], v[144:147], v[190:193], v[48:51]
	v_mfma_f32_16x16x32_bf16 v[44:47], v[158:161], v[190:193], v[44:47]
	v_mfma_f32_16x16x32_bf16 v[32:35], v[144:147], v[198:201], v[32:35]
	v_mfma_f32_16x16x32_bf16 v[28:31], v[158:161], v[198:201], v[28:31]
	v_mfma_f32_16x16x32_bf16 v[16:19], v[144:147], v[210:213], v[16:19]
	v_mfma_f32_16x16x32_bf16 v[12:15], v[158:161], v[210:213], v[12:15]
	v_mfma_f32_16x16x32_bf16 v[64:67], v[154:157], v[186:189], v[64:67]
	v_mfma_f32_16x16x32_bf16 v[60:63], v[162:165], v[186:189], v[60:63]
	v_mfma_f32_16x16x32_bf16 v[48:51], v[154:157], v[194:197], v[48:51]
	v_mfma_f32_16x16x32_bf16 v[44:47], v[162:165], v[194:197], v[44:47]
	v_mfma_f32_16x16x32_bf16 v[32:35], v[154:157], v[202:205], v[32:35]
	v_mfma_f32_16x16x32_bf16 v[28:31], v[162:165], v[202:205], v[28:31]
	v_mfma_f32_16x16x32_bf16 v[16:19], v[154:157], v[218:221], v[16:19]
	v_mfma_f32_16x16x32_bf16 v[12:15], v[162:165], v[218:221], v[12:15]
	v_mfma_f32_16x16x32_bf16 v[56:59], v[166:169], v[182:185], v[56:59]
	v_mfma_f32_16x16x32_bf16 v[52:55], v[174:177], v[182:185], v[52:55]
	v_mfma_f32_16x16x32_bf16 v[40:43], v[166:169], v[190:193], v[40:43]
	v_mfma_f32_16x16x32_bf16 v[36:39], v[174:177], v[190:193], v[36:39]
	v_mfma_f32_16x16x32_bf16 v[24:27], v[166:169], v[198:201], v[24:27]
	v_mfma_f32_16x16x32_bf16 v[20:23], v[174:177], v[198:201], v[20:23]
	v_mfma_f32_16x16x32_bf16 v[8:11], v[166:169], v[210:213], v[8:11]
	v_mfma_f32_16x16x32_bf16 v[4:7], v[174:177], v[210:213], v[4:7]
	v_mfma_f32_16x16x32_bf16 v[56:59], v[170:173], v[186:189], v[56:59]
	v_mfma_f32_16x16x32_bf16 v[52:55], v[178:181], v[186:189], v[52:55]
	v_mfma_f32_16x16x32_bf16 v[40:43], v[170:173], v[194:197], v[40:43]
	v_mfma_f32_16x16x32_bf16 v[36:39], v[178:181], v[194:197], v[36:39]
	v_mfma_f32_16x16x32_bf16 v[24:27], v[170:173], v[202:205], v[24:27]
	v_mfma_f32_16x16x32_bf16 v[20:23], v[178:181], v[202:205], v[20:23]
	v_mfma_f32_16x16x32_bf16 v[8:11], v[170:173], v[218:221], v[8:11]
	v_mfma_f32_16x16x32_bf16 v[4:7], v[178:181], v[218:221], v[4:7]
	s_add_i32 s53, s53, 2
	s_add_u32 s4, s4, 0x100
	s_addc_u32 s5, s5, 0
	s_add_u32 s51, s51, 0x100
	s_addc_u32 s52, s52, 0
	s_cmp_gt_u32 s53, 13
	s_barrier
	s_cbranch_scc0 .LBB0_2540
	s_and_b64 vcc, exec, s[16:17]
	s_cbranch_vccz .LBB0_2543
	s_barrier

.LBB0_2645:
	v_add_u32_e32 v148, s61, v150
	ds_read_b128 v[144:147], v148
	ds_read_b128 v[152:155], v148 offset:1024
	ds_read_b128 v[156:159], v148 offset:2048
	ds_read_b128 v[160:163], v148 offset:3072
	v_add_u32_e32 v148, s77, v150
	ds_read_b128 v[164:167], v148
	ds_read_b128 v[168:171], v148 offset:1024
	ds_read_b128 v[172:175], v148 offset:2048
	ds_read_b128 v[176:179], v148 offset:3072
	s_add_u32 s6, s4, 0xfff00080
	s_addc_u32 s7, s5, -1
	s_cmp_eq_u32 s51, 60
	s_cselect_b32 s9, s29, s7
	s_cselect_b32 s8, s49, s6
	s_cselect_b32 s7, s19, s50
	s_cselect_b32 s6, s18, s27
	v_lshl_add_u64 v[148:149], s[4:5], 0, v[140:141]
	s_add_i32 m0, s17, 0xc000
	ds_read_b128 v[180:183], v151
	ds_read_b128 v[184:187], v151 offset:1024
	ds_read_b128 v[188:191], v151 offset:2048
	ds_read_b128 v[192:195], v151 offset:3072
	ds_read_b128 v[196:199], v151 offset:4096
	ds_read_b128 v[200:203], v151 offset:5120
	ds_read_b128 v[204:207], v151 offset:6144
	ds_read_b128 v[210:213], v151 offset:7168
	global_load_lds_dwordx4 v[148:149], off
	v_lshl_add_u64 v[148:149], s[4:5], 0, v[142:143]
	s_add_i32 m0, s17, 0xe000
	s_nop 0
	global_load_lds_dwordx4 v[148:149], off
	s_waitcnt vmcnt(8)
	s_waitcnt lgkmcnt(0)
	s_barrier
	s_waitcnt lgkmcnt(0)
	v_mfma_f32_16x16x32_bf16 v[128:131], v[144:147], v[180:183], v[128:131]
	v_mfma_f32_16x16x32_bf16 v[124:127], v[156:159], v[180:183], v[124:127]
	v_mfma_f32_16x16x32_bf16 v[112:115], v[144:147], v[188:191], v[112:115]
	v_mfma_f32_16x16x32_bf16 v[108:111], v[156:159], v[188:191], v[108:111]
	v_mfma_f32_16x16x32_bf16 v[96:99], v[144:147], v[196:199], v[96:99]
	v_mfma_f32_16x16x32_bf16 v[92:95], v[156:159], v[196:199], v[92:95]
	v_mfma_f32_16x16x32_bf16 v[80:83], v[144:147], v[204:207], v[80:83]
	v_mfma_f32_16x16x32_bf16 v[76:79], v[156:159], v[204:207], v[76:79]
	v_mfma_f32_16x16x32_bf16 v[128:131], v[152:155], v[184:187], v[128:131]
	v_mfma_f32_16x16x32_bf16 v[124:127], v[160:163], v[184:187], v[124:127]
	v_mfma_f32_16x16x32_bf16 v[112:115], v[152:155], v[192:195], v[112:115]
	v_mfma_f32_16x16x32_bf16 v[108:111], v[160:163], v[192:195], v[108:111]
	v_mfma_f32_16x16x32_bf16 v[96:99], v[152:155], v[200:203], v[96:99]
	v_mfma_f32_16x16x32_bf16 v[92:95], v[160:163], v[200:203], v[92:95]
	v_mfma_f32_16x16x32_bf16 v[80:83], v[152:155], v[210:213], v[80:83]
	v_mfma_f32_16x16x32_bf16 v[76:79], v[160:163], v[210:213], v[76:79]
	v_mfma_f32_16x16x32_bf16 v[120:123], v[164:167], v[180:183], v[120:123]
	v_mfma_f32_16x16x32_bf16 v[116:119], v[172:175], v[180:183], v[116:119]
	v_mfma_f32_16x16x32_bf16 v[104:107], v[164:167], v[188:191], v[104:107]
	v_mfma_f32_16x16x32_bf16 v[100:103], v[172:175], v[188:191], v[100:103]
	v_mfma_f32_16x16x32_bf16 v[88:91], v[164:167], v[196:199], v[88:91]
	v_mfma_f32_16x16x32_bf16 v[84:87], v[172:175], v[196:199], v[84:87]
	v_mfma_f32_16x16x32_bf16 v[72:75], v[164:167], v[204:207], v[72:75]
	v_mfma_f32_16x16x32_bf16 v[68:71], v[172:175], v[204:207], v[68:71]
	v_mfma_f32_16x16x32_bf16 v[120:123], v[168:171], v[184:187], v[120:123]
	v_mfma_f32_16x16x32_bf16 v[116:119], v[176:179], v[184:187], v[116:119]
	v_mfma_f32_16x16x32_bf16 v[104:107], v[168:171], v[192:195], v[104:107]
	v_mfma_f32_16x16x32_bf16 v[100:103], v[176:179], v[192:195], v[100:103]
	v_mfma_f32_16x16x32_bf16 v[88:91], v[168:171], v[200:203], v[88:91]
	v_mfma_f32_16x16x32_bf16 v[84:87], v[176:179], v[200:203], v[84:87]
	v_mfma_f32_16x16x32_bf16 v[72:75], v[168:171], v[210:213], v[72:75]
	v_mfma_f32_16x16x32_bf16 v[68:71], v[176:179], v[210:213], v[68:71]
	s_barrier
	s_add_i32 s52, s61, s37
	v_lshl_add_u64 v[148:149], s[6:7], 0, v[136:137]
	s_mov_b32 m0, s52
	ds_read_b128 v[180:183], v151 offset:16384
	ds_read_b128 v[184:187], v151 offset:17408
	ds_read_b128 v[188:191], v151 offset:18432
	ds_read_b128 v[192:195], v151 offset:19456
	ds_read_b128 v[196:199], v151 offset:20480
	ds_read_b128 v[200:203], v151 offset:21504
	ds_read_b128 v[204:207], v151 offset:22528
	ds_read_b128 v[210:213], v151 offset:23552
	global_load_lds_dwordx4 v[148:149], off
	s_add_i32 m0, s52, 0x2000
	s_add_u32 s52, s6, 0x100000
	v_lshl_add_u64 v[218:219], s[6:7], 0, v[132:133]
	s_addc_u32 s53, s7, 0
	s_add_i32 s58, s77, s37
	global_load_lds_dwordx4 v[218:219], off
	v_lshl_add_u64 v[220:221], s[52:53], 0, v[136:137]
	s_mov_b32 m0, s58
	v_lshl_add_u64 v[222:223], s[8:9], 0, v[134:135]
	global_load_lds_dwordx4 v[220:221], off
	v_lshl_add_u64 v[220:221], s[52:53], 0, v[132:133]
	s_add_i32 m0, s58, 0x2000
	s_nop 0
	global_load_lds_dwordx4 v[220:221], off
	v_lshl_add_u64 v[220:221], s[8:9], 0, v[138:139]
	s_mov_b32 m0, s17
	s_nop 0
	global_load_lds_dwordx4 v[220:221], off
	s_mov_b32 m0, s39
	s_nop 0
	global_load_lds_dwordx4 v[222:223], off
	s_waitcnt vmcnt(8)
	s_waitcnt lgkmcnt(0)
	s_barrier
	s_waitcnt lgkmcnt(0)
	v_mfma_f32_16x16x32_bf16 v[64:67], v[144:147], v[180:183], v[64:67]
	v_mfma_f32_16x16x32_bf16 v[60:63], v[156:159], v[180:183], v[60:63]
	v_mfma_f32_16x16x32_bf16 v[48:51], v[144:147], v[188:191], v[48:51]
	v_mfma_f32_16x16x32_bf16 v[44:47], v[156:159], v[188:191], v[44:47]
	v_mfma_f32_16x16x32_bf16 v[32:35], v[144:147], v[196:199], v[32:35]
	v_mfma_f32_16x16x32_bf16 v[28:31], v[156:159], v[196:199], v[28:31]
	v_mfma_f32_16x16x32_bf16 v[16:19], v[144:147], v[204:207], v[16:19]
	v_mfma_f32_16x16x32_bf16 v[12:15], v[156:159], v[204:207], v[12:15]
	v_mfma_f32_16x16x32_bf16 v[64:67], v[152:155], v[184:187], v[64:67]
	v_mfma_f32_16x16x32_bf16 v[60:63], v[160:163], v[184:187], v[60:63]
	v_mfma_f32_16x16x32_bf16 v[48:51], v[152:155], v[192:195], v[48:51]
	v_mfma_f32_16x16x32_bf16 v[44:47], v[160:163], v[192:195], v[44:47]
	v_mfma_f32_16x16x32_bf16 v[32:35], v[152:155], v[200:203], v[32:35]
	v_mfma_f32_16x16x32_bf16 v[28:31], v[160:163], v[200:203], v[28:31]
	v_mfma_f32_16x16x32_bf16 v[16:19], v[152:155], v[210:213], v[16:19]
	v_mfma_f32_16x16x32_bf16 v[12:15], v[160:163], v[210:213], v[12:15]
	v_mfma_f32_16x16x32_bf16 v[56:59], v[164:167], v[180:183], v[56:59]
	v_mfma_f32_16x16x32_bf16 v[52:55], v[172:175], v[180:183], v[52:55]
	v_mfma_f32_16x16x32_bf16 v[40:43], v[164:167], v[188:191], v[40:43]
	v_mfma_f32_16x16x32_bf16 v[36:39], v[172:175], v[188:191], v[36:39]
	v_mfma_f32_16x16x32_bf16 v[24:27], v[164:167], v[196:199], v[24:27]
	v_mfma_f32_16x16x32_bf16 v[20:23], v[172:175], v[196:199], v[20:23]
	v_mfma_f32_16x16x32_bf16 v[8:11], v[164:167], v[204:207], v[8:11]
	v_mfma_f32_16x16x32_bf16 v[4:7], v[172:175], v[204:207], v[4:7]
	v_mfma_f32_16x16x32_bf16 v[56:59], v[168:171], v[184:187], v[56:59]
	v_mfma_f32_16x16x32_bf16 v[52:55], v[176:179], v[184:187], v[52:55]
	v_mfma_f32_16x16x32_bf16 v[40:43], v[168:171], v[192:195], v[40:43]
	v_mfma_f32_16x16x32_bf16 v[36:39], v[176:179], v[192:195], v[36:39]
	v_mfma_f32_16x16x32_bf16 v[24:27], v[168:171], v[200:203], v[24:27]
	v_mfma_f32_16x16x32_bf16 v[20:23], v[176:179], v[200:203], v[20:23]
	v_mfma_f32_16x16x32_bf16 v[8:11], v[168:171], v[210:213], v[8:11]
	v_mfma_f32_16x16x32_bf16 v[4:7], v[176:179], v[210:213], v[4:7]
	s_barrier
	v_add_u32_e32 v160, s79, v150
	v_add_u32_e32 v176, s80, v150
	ds_read_b128 v[144:147], v160
	ds_read_b128 v[152:155], v160 offset:1024
	ds_read_b128 v[156:159], v160 offset:2048
	ds_read_b128 v[160:163], v160 offset:3072
	ds_read_b128 v[164:167], v176
	ds_read_b128 v[168:171], v176 offset:1024
	ds_read_b128 v[172:175], v176 offset:2048
	ds_read_b128 v[176:179], v176 offset:3072
	s_add_u32 s8, s8, 0x100000
	s_addc_u32 s9, s9, 0
	s_mov_b32 m0, s40
	v_lshl_add_u64 v[224:225], s[8:9], 0, v[138:139]
	ds_read_b128 v[180:183], v151 offset:32768
	ds_read_b128 v[184:187], v151 offset:33792
	ds_read_b128 v[188:191], v151 offset:34816
	ds_read_b128 v[192:195], v151 offset:35840
	ds_read_b128 v[196:199], v151 offset:36864
	ds_read_b128 v[200:203], v151 offset:37888
	ds_read_b128 v[204:207], v151 offset:38912
	ds_read_b128 v[210:213], v151 offset:39936
	global_load_lds_dwordx4 v[224:225], off
	v_lshl_add_u64 v[224:225], s[8:9], 0, v[134:135]
	s_mov_b32 m0, s41
	s_nop 0
	global_load_lds_dwordx4 v[224:225], off
	s_waitcnt vmcnt(8)
	s_waitcnt lgkmcnt(0)
	s_barrier
	s_waitcnt lgkmcnt(0)
	v_mfma_f32_16x16x32_bf16 v[128:131], v[144:147], v[180:183], v[128:131]
	v_mfma_f32_16x16x32_bf16 v[124:127], v[156:159], v[180:183], v[124:127]
	v_mfma_f32_16x16x32_bf16 v[112:115], v[144:147], v[188:191], v[112:115]
	v_mfma_f32_16x16x32_bf16 v[108:111], v[156:159], v[188:191], v[108:111]
	v_mfma_f32_16x16x32_bf16 v[96:99], v[144:147], v[196:199], v[96:99]
	v_mfma_f32_16x16x32_bf16 v[92:95], v[156:159], v[196:199], v[92:95]
	v_mfma_f32_16x16x32_bf16 v[80:83], v[144:147], v[204:207], v[80:83]
	v_mfma_f32_16x16x32_bf16 v[76:79], v[156:159], v[204:207], v[76:79]
	v_mfma_f32_16x16x32_bf16 v[128:131], v[152:155], v[184:187], v[128:131]
	v_mfma_f32_16x16x32_bf16 v[124:127], v[160:163], v[184:187], v[124:127]
	v_mfma_f32_16x16x32_bf16 v[112:115], v[152:155], v[192:195], v[112:115]
	v_mfma_f32_16x16x32_bf16 v[108:111], v[160:163], v[192:195], v[108:111]
	v_mfma_f32_16x16x32_bf16 v[96:99], v[152:155], v[200:203], v[96:99]
	v_mfma_f32_16x16x32_bf16 v[92:95], v[160:163], v[200:203], v[92:95]
	v_mfma_f32_16x16x32_bf16 v[80:83], v[152:155], v[210:213], v[80:83]
	v_mfma_f32_16x16x32_bf16 v[76:79], v[160:163], v[210:213], v[76:79]
	v_mfma_f32_16x16x32_bf16 v[120:123], v[164:167], v[180:183], v[120:123]
	v_mfma_f32_16x16x32_bf16 v[116:119], v[172:175], v[180:183], v[116:119]
	v_mfma_f32_16x16x32_bf16 v[104:107], v[164:167], v[188:191], v[104:107]
	v_mfma_f32_16x16x32_bf16 v[100:103], v[172:175], v[188:191], v[100:103]
	v_mfma_f32_16x16x32_bf16 v[88:91], v[164:167], v[196:199], v[88:91]
	v_mfma_f32_16x16x32_bf16 v[84:87], v[172:175], v[196:199], v[84:87]
	v_mfma_f32_16x16x32_bf16 v[72:75], v[164:167], v[204:207], v[72:75]
	v_mfma_f32_16x16x32_bf16 v[68:71], v[172:175], v[204:207], v[68:71]
	v_mfma_f32_16x16x32_bf16 v[120:123], v[168:171], v[184:187], v[120:123]
	v_mfma_f32_16x16x32_bf16 v[116:119], v[176:179], v[184:187], v[116:119]
	v_mfma_f32_16x16x32_bf16 v[104:107], v[168:171], v[192:195], v[104:107]
	v_mfma_f32_16x16x32_bf16 v[100:103], v[176:179], v[192:195], v[100:103]
	v_mfma_f32_16x16x32_bf16 v[88:91], v[168:171], v[200:203], v[88:91]
	v_mfma_f32_16x16x32_bf16 v[84:87], v[176:179], v[200:203], v[84:87]
	v_mfma_f32_16x16x32_bf16 v[72:75], v[168:171], v[210:213], v[72:75]
	v_mfma_f32_16x16x32_bf16 v[68:71], v[176:179], v[210:213], v[68:71]
	s_barrier
	s_add_i32 s8, s79, s37
	v_lshl_add_u64 v[148:149], v[148:149], 0, s[56:57]
	s_mov_b32 m0, s8
	ds_read_b128 v[180:183], v151 offset:49152
	ds_read_b128 v[184:187], v151 offset:50176
	ds_read_b128 v[188:191], v151 offset:51200
	ds_read_b128 v[192:195], v151 offset:52224
	ds_read_b128 v[196:199], v151 offset:53248
	ds_read_b128 v[200:203], v151 offset:54272
	ds_read_b128 v[204:207], v151 offset:55296
	ds_read_b128 v[210:213], v151 offset:56320
	global_load_lds_dwordx4 v[148:149], off
	s_add_i32 m0, s8, 0x2000
	s_add_u32 s6, s6, 0x100080
	v_lshl_add_u64 v[148:149], v[218:219], 0, s[56:57]
	s_addc_u32 s7, s7, 0
	s_add_i32 s8, s80, s37
	global_load_lds_dwordx4 v[148:149], off
	v_lshl_add_u64 v[148:149], s[6:7], 0, v[136:137]
	s_mov_b32 m0, s8
	s_nop 0
	global_load_lds_dwordx4 v[148:149], off
	v_lshl_add_u64 v[148:149], s[6:7], 0, v[132:133]
	s_add_i32 m0, s8, 0x2000
	s_nop 0
	global_load_lds_dwordx4 v[148:149], off
	v_lshl_add_u64 v[148:149], v[220:221], 0, s[56:57]
	s_mov_b32 m0, s43
	s_nop 0
	global_load_lds_dwordx4 v[148:149], off
	v_lshl_add_u64 v[148:149], v[222:223], 0, s[56:57]
	s_mov_b32 m0, s44
	s_nop 0
	global_load_lds_dwordx4 v[148:149], off
	s_waitcnt vmcnt(8)
	s_waitcnt lgkmcnt(0)
	s_barrier
	s_waitcnt lgkmcnt(0)
	v_mfma_f32_16x16x32_bf16 v[64:67], v[144:147], v[180:183], v[64:67]
	v_mfma_f32_16x16x32_bf16 v[60:63], v[156:159], v[180:183], v[60:63]
	v_mfma_f32_16x16x32_bf16 v[48:51], v[144:147], v[188:191], v[48:51]
	v_mfma_f32_16x16x32_bf16 v[44:47], v[156:159], v[188:191], v[44:47]
	v_mfma_f32_16x16x32_bf16 v[32:35], v[144:147], v[196:199], v[32:35]
	v_mfma_f32_16x16x32_bf16 v[28:31], v[156:159], v[196:199], v[28:31]
	v_mfma_f32_16x16x32_bf16 v[16:19], v[144:147], v[204:207], v[16:19]
	v_mfma_f32_16x16x32_bf16 v[12:15], v[156:159], v[204:207], v[12:15]
	v_mfma_f32_16x16x32_bf16 v[64:67], v[152:155], v[184:187], v[64:67]
	v_mfma_f32_16x16x32_bf16 v[60:63], v[160:163], v[184:187], v[60:63]
	v_mfma_f32_16x16x32_bf16 v[48:51], v[152:155], v[192:195], v[48:51]
	v_mfma_f32_16x16x32_bf16 v[44:47], v[160:163], v[192:195], v[44:47]
	v_mfma_f32_16x16x32_bf16 v[32:35], v[152:155], v[200:203], v[32:35]
	v_mfma_f32_16x16x32_bf16 v[28:31], v[160:163], v[200:203], v[28:31]
	v_mfma_f32_16x16x32_bf16 v[16:19], v[152:155], v[210:213], v[16:19]
	v_mfma_f32_16x16x32_bf16 v[12:15], v[160:163], v[210:213], v[12:15]
	v_mfma_f32_16x16x32_bf16 v[56:59], v[164:167], v[180:183], v[56:59]
	v_mfma_f32_16x16x32_bf16 v[52:55], v[172:175], v[180:183], v[52:55]
	v_mfma_f32_16x16x32_bf16 v[40:43], v[164:167], v[188:191], v[40:43]
	v_mfma_f32_16x16x32_bf16 v[36:39], v[172:175], v[188:191], v[36:39]
	v_mfma_f32_16x16x32_bf16 v[24:27], v[164:167], v[196:199], v[24:27]
	v_mfma_f32_16x16x32_bf16 v[20:23], v[172:175], v[196:199], v[20:23]
	v_mfma_f32_16x16x32_bf16 v[8:11], v[164:167], v[204:207], v[8:11]
	v_mfma_f32_16x16x32_bf16 v[4:7], v[172:175], v[204:207], v[4:7]
	v_mfma_f32_16x16x32_bf16 v[56:59], v[168:171], v[184:187], v[56:59]
	v_mfma_f32_16x16x32_bf16 v[52:55], v[176:179], v[184:187], v[52:55]
	v_mfma_f32_16x16x32_bf16 v[40:43], v[168:171], v[192:195], v[40:43]
	v_mfma_f32_16x16x32_bf16 v[36:39], v[176:179], v[192:195], v[36:39]
	v_mfma_f32_16x16x32_bf16 v[24:27], v[168:171], v[200:203], v[24:27]
	v_mfma_f32_16x16x32_bf16 v[20:23], v[176:179], v[200:203], v[20:23]
	v_mfma_f32_16x16x32_bf16 v[8:11], v[168:171], v[210:213], v[8:11]
	v_mfma_f32_16x16x32_bf16 v[4:7], v[176:179], v[210:213], v[4:7]
	s_add_i32 s51, s51, 2
	s_add_u32 s4, s4, 0x100
	s_addc_u32 s5, s5, 0
	s_add_u32 s27, s27, 0x100
	s_addc_u32 s50, s50, 0
	s_cmp_gt_u32 s51, 61
	s_barrier
	s_cbranch_scc0 .LBB0_2645
	s_and_b64 vcc, exec, s[24:25]
	s_cbranch_vccz .LBB0_2648
	s_barrier
